# MLP2A/MLP2B on the 256-workgroup path: one hand-written 256x256 16x16x32 tile per workgroup (tile index remapped, same output set as the two 256x128 rounds), 16-byte residual loads and stores; OUT0/OU
# speedup vs baseline: 1.1092x; 1.0398x over previous
.LBB0_68:
	s_andn2_b64 vcc, exec, s[26:27]
	s_mov_b64 s[26:27], 0
	s_cbranch_vccnz .LBB0_107
	v_readlane_b32 s24, v236, 3
	v_readlane_b32 s25, v236, 4
	s_andn2_b64 vcc, exec, s[24:25]
	s_cbranch_vccnz .LBB0_88
	s_add_u32 s26, s46, 0xaa08000
	s_addc_u32 s27, s47, 0
	v_readlane_b32 s24, v236, 5
	v_readlane_b32 s25, v236, 9
	s_lshr_b32 s28, s25, 2
	s_lshl_b32 s28, s28, 3
	s_and_b32 s25, s25, 3
	s_lshl_b32 s25, s25, 1
	s_or_b32 s25, s25, s28
	s_branch .LBB0_72

.LBB0_76:
	s_waitcnt lgkmcnt(0)
	s_lshl_b64 s[36:37], s[90:91], 13
	s_add_u32 s36, s36, s28
	s_addc_u32 s37, s37, s29
	s_and_b32 s30, s25, 7
	s_lshl_b32 s30, s30, 7
	s_lshl_b32 s68, s30, 13
	s_add_u32 s52, s50, s68
	s_addc_u32 s53, s51, 0
	v_readfirstlane_b32 s68, v200
	s_lshr_b32 s68, s68, 6
	s_lshl_b32 s31, s68, 11
	s_add_u32 s31, s31, 16
	s_lshl_b32 s68, s68, 18
	s_add_u32 s36, s36, s68
	s_addc_u32 s37, s37, 0
	s_add_u32 s52, s52, s68
	s_addc_u32 s53, s53, 0
	v_bfe_u32 v173, v200, 4, 2
	v_sub_u32_e32 v173, 0, v173
	v_and_b32_e32 v173, 3, v173
	v_and_b32_e32 v172, 3, v200
	v_xor_b32_e32 v172, v172, v173
	v_bfe_u32 v173, v200, 2, 4
	v_lshlrev_b32_e32 v173, 13, v173
	v_lshl_or_b32 v170, v172, 4, v173
	v_add_u32_e32 v171, 0x20000, v170
	v_bfe_u32 v172, v200, 2, 2
	v_sub_u32_e32 v172, 0, v172
	v_and_b32_e32 v172, 3, v172
	v_bfe_u32 v173, v200, 4, 2
	v_xor_b32_e32 v172, v172, v173
	v_and_b32_e32 v173, 15, v200
	v_bfe_u32 v174, v200, 8, 1
	v_lshl_or_b32 v174, v174, 7, v173
	v_lshlrev_b32_e32 v174, 6, v174
	v_lshl_or_b32 v164, v172, 4, v174
	v_bfe_u32 v174, v200, 6, 2
	v_lshl_or_b32 v174, v174, 6, v173
	v_lshlrev_b32_e32 v174, 6, v174
	v_lshl_or_b32 v165, v172, 4, v174
	v_add_u32_e32 v165, 0x4000, v165
	v_bfe_u32 v172, v200, 6, 2
	v_bfe_u32 v173, v200, 4, 2
	v_lshlrev_b32_e32 v172, 6, v172
	v_lshl_or_b32 v172, v173, 2, v172
	v_add_u32_e32 v172, s30, v172
	v_lshlrev_b32_e32 v172, 2, v172
	global_load_dwordx4 v[132:135], v172, s[44:45]
	global_load_dwordx4 v[136:139], v172, s[44:45] offset:64
	global_load_dwordx4 v[140:143], v172, s[44:45] offset:128
	global_load_dwordx4 v[144:147], v172, s[44:45] offset:192
	s_mov_b32 s34, s31
	s_mov_b32 m0, s34
	s_nop 0
	global_load_lds_dwordx4 v170, s[36:37]
	s_add_u32 m0, s34, 0x400
	s_nop 0
	global_load_lds_dwordx4 v171, s[36:37]
	s_add_u32 m0, s34, 0x4000
	s_nop 0
	global_load_lds_dwordx4 v170, s[52:53]
	s_add_u32 m0, s34, 0x4400
	s_nop 0
	global_load_lds_dwordx4 v171, s[52:53]
	s_add_u32 s36, s36, 64
	s_addc_u32 s37, s37, 0
	s_add_u32 s52, s52, 64
	s_addc_u32 s53, s53, 0
	s_add_u32 s34, s31, 0x8000
	s_mov_b32 m0, s34
	s_nop 0
	global_load_lds_dwordx4 v170, s[36:37]
	s_add_u32 m0, s34, 0x400
	s_nop 0
	global_load_lds_dwordx4 v171, s[36:37]
	s_add_u32 m0, s34, 0x4000
	s_nop 0
	global_load_lds_dwordx4 v170, s[52:53]
	s_add_u32 m0, s34, 0x4400
	s_nop 0
	global_load_lds_dwordx4 v171, s[52:53]
	s_add_u32 s36, s36, 64
	s_addc_u32 s37, s37, 0
	s_add_u32 s52, s52, 64
	s_addc_u32 s53, s53, 0
	s_add_u32 s34, s31, 0x10000
	s_mov_b32 m0, s34
	s_nop 0
	global_load_lds_dwordx4 v170, s[36:37]
	s_add_u32 m0, s34, 0x400
	s_nop 0
	global_load_lds_dwordx4 v171, s[36:37]
	s_add_u32 m0, s34, 0x4000
	s_nop 0
	global_load_lds_dwordx4 v170, s[52:53]
	s_add_u32 m0, s34, 0x4400
	s_nop 0
	global_load_lds_dwordx4 v171, s[52:53]
	s_add_u32 s36, s36, 64
	s_addc_u32 s37, s37, 0
	s_add_u32 s52, s52, 64
	s_addc_u32 s53, s53, 0
	s_add_u32 s34, s31, 0x18000
	s_mov_b32 m0, s34
	s_nop 0
	global_load_lds_dwordx4 v170, s[36:37]
	s_add_u32 m0, s34, 0x400
	s_nop 0
	global_load_lds_dwordx4 v171, s[36:37]
	s_add_u32 m0, s34, 0x4000
	s_nop 0
	global_load_lds_dwordx4 v170, s[52:53]
	s_add_u32 m0, s34, 0x4400
	s_nop 0
	global_load_lds_dwordx4 v171, s[52:53]
	s_add_u32 s36, s36, 64
	s_addc_u32 s37, s37, 0
	s_add_u32 s52, s52, 64
	s_addc_u32 s53, s53, 0
	s_waitcnt vmcnt(16)
	v_mov_b32_e32 v4, v132
	v_mov_b32_e32 v5, v133
	v_mov_b32_e32 v6, v134
	v_mov_b32_e32 v7, v135
	v_mov_b32_e32 v8, v136
	v_mov_b32_e32 v9, v137
	v_mov_b32_e32 v10, v138
	v_mov_b32_e32 v11, v139
	v_mov_b32_e32 v12, v140
	v_mov_b32_e32 v13, v141
	v_mov_b32_e32 v14, v142
	v_mov_b32_e32 v15, v143
	v_mov_b32_e32 v16, v144
	v_mov_b32_e32 v17, v145
	v_mov_b32_e32 v18, v146
	v_mov_b32_e32 v19, v147
	v_mov_b32_e32 v20, v132
	v_mov_b32_e32 v21, v133
	v_mov_b32_e32 v22, v134
	v_mov_b32_e32 v23, v135
	v_mov_b32_e32 v24, v136
	v_mov_b32_e32 v25, v137
	v_mov_b32_e32 v26, v138
	v_mov_b32_e32 v27, v139
	v_mov_b32_e32 v28, v140
	v_mov_b32_e32 v29, v141
	v_mov_b32_e32 v30, v142
	v_mov_b32_e32 v31, v143
	v_mov_b32_e32 v32, v144
	v_mov_b32_e32 v33, v145
	v_mov_b32_e32 v34, v146
	v_mov_b32_e32 v35, v147
	v_mov_b32_e32 v36, v132
	v_mov_b32_e32 v37, v133
	v_mov_b32_e32 v38, v134
	v_mov_b32_e32 v39, v135
	v_mov_b32_e32 v40, v136
	v_mov_b32_e32 v41, v137
	v_mov_b32_e32 v42, v138
	v_mov_b32_e32 v43, v139
	v_mov_b32_e32 v44, v140
	v_mov_b32_e32 v45, v141
	v_mov_b32_e32 v46, v142
	v_mov_b32_e32 v47, v143
	v_mov_b32_e32 v48, v144
	v_mov_b32_e32 v49, v145
	v_mov_b32_e32 v50, v146
	v_mov_b32_e32 v51, v147
	v_mov_b32_e32 v52, v132
	v_mov_b32_e32 v53, v133
	v_mov_b32_e32 v54, v134
	v_mov_b32_e32 v55, v135
	v_mov_b32_e32 v56, v136
	v_mov_b32_e32 v57, v137
	v_mov_b32_e32 v58, v138
	v_mov_b32_e32 v59, v139
	v_mov_b32_e32 v60, v140
	v_mov_b32_e32 v61, v141
	v_mov_b32_e32 v62, v142
	v_mov_b32_e32 v63, v143
	v_mov_b32_e32 v64, v144
	v_mov_b32_e32 v65, v145
	v_mov_b32_e32 v66, v146
	v_mov_b32_e32 v67, v147
	v_mov_b32_e32 v68, v132
	v_mov_b32_e32 v69, v133
	v_mov_b32_e32 v70, v134
	v_mov_b32_e32 v71, v135
	v_mov_b32_e32 v72, v136
	v_mov_b32_e32 v73, v137
	v_mov_b32_e32 v74, v138
	v_mov_b32_e32 v75, v139
	v_mov_b32_e32 v76, v140
	v_mov_b32_e32 v77, v141
	v_mov_b32_e32 v78, v142
	v_mov_b32_e32 v79, v143
	v_mov_b32_e32 v80, v144
	v_mov_b32_e32 v81, v145
	v_mov_b32_e32 v82, v146
	v_mov_b32_e32 v83, v147
	v_mov_b32_e32 v84, v132
	v_mov_b32_e32 v85, v133
	v_mov_b32_e32 v86, v134
	v_mov_b32_e32 v87, v135
	v_mov_b32_e32 v88, v136
	v_mov_b32_e32 v89, v137
	v_mov_b32_e32 v90, v138
	v_mov_b32_e32 v91, v139
	v_mov_b32_e32 v92, v140
	v_mov_b32_e32 v93, v141
	v_mov_b32_e32 v94, v142
	v_mov_b32_e32 v95, v143
	v_mov_b32_e32 v96, v144
	v_mov_b32_e32 v97, v145
	v_mov_b32_e32 v98, v146
	v_mov_b32_e32 v99, v147
	v_mov_b32_e32 v100, v132
	v_mov_b32_e32 v101, v133
	v_mov_b32_e32 v102, v134
	v_mov_b32_e32 v103, v135
	v_mov_b32_e32 v104, v136
	v_mov_b32_e32 v105, v137
	v_mov_b32_e32 v106, v138
	v_mov_b32_e32 v107, v139
	v_mov_b32_e32 v108, v140
	v_mov_b32_e32 v109, v141
	v_mov_b32_e32 v110, v142
	v_mov_b32_e32 v111, v143
	v_mov_b32_e32 v112, v144
	v_mov_b32_e32 v113, v145
	v_mov_b32_e32 v114, v146
	v_mov_b32_e32 v115, v147
	v_mov_b32_e32 v116, v132
	v_mov_b32_e32 v117, v133
	v_mov_b32_e32 v118, v134
	v_mov_b32_e32 v119, v135
	v_mov_b32_e32 v120, v136
	v_mov_b32_e32 v121, v137
	v_mov_b32_e32 v122, v138
	v_mov_b32_e32 v123, v139
	v_mov_b32_e32 v124, v140
	v_mov_b32_e32 v125, v141
	v_mov_b32_e32 v126, v142
	v_mov_b32_e32 v127, v143
	v_mov_b32_e32 v128, v144
	v_mov_b32_e32 v129, v145
	v_mov_b32_e32 v130, v146
	v_mov_b32_e32 v131, v147
	s_waitcnt vmcnt(12)
	s_barrier
	s_mov_b32 s32, 0
	s_mov_b32 s65, 0
	s_nop 1
	v_add_u32_e32 v168, s32, v165
	v_add_u32_e32 v169, s32, v164
	ds_read_b128 v[132:135], v168 offset:16
	ds_read_b128 v[136:139], v168 offset:1040
	ds_read_b128 v[140:143], v168 offset:2064
	ds_read_b128 v[144:147], v168 offset:3088
	ds_read_b128 v[184:187], v169 offset:16
	ds_read_b128 v[188:191], v169 offset:1040
	ds_read_b128 v[192:195], v169 offset:2064
	ds_read_b128 v[196:199], v169 offset:3088
	s_waitcnt lgkmcnt(0)
.Lt_mlp2b:
	v_add_u32_e32 v169, s32, v164
	v_mfma_f32_16x16x32_f16 v[4:7], v[132:135], v[184:187], v[4:7]
	ds_read_b128 v[238:241], v169 offset:4112
	v_mfma_f32_16x16x32_f16 v[8:11], v[136:139], v[184:187], v[8:11]
	ds_read_b128 v[242:245], v169 offset:5136
	v_mfma_f32_16x16x32_f16 v[12:15], v[140:143], v[184:187], v[12:15]
	ds_read_b128 v[246:249], v169 offset:6160
	v_mfma_f32_16x16x32_f16 v[16:19], v[144:147], v[184:187], v[16:19]
	ds_read_b128 v[250:253], v169 offset:7184
	v_mfma_f32_16x16x32_f16 v[20:23], v[132:135], v[188:191], v[20:23]
	v_mfma_f32_16x16x32_f16 v[24:27], v[136:139], v[188:191], v[24:27]
	v_mfma_f32_16x16x32_f16 v[28:31], v[140:143], v[188:191], v[28:31]
	v_mfma_f32_16x16x32_f16 v[32:35], v[144:147], v[188:191], v[32:35]
	v_mfma_f32_16x16x32_f16 v[36:39], v[132:135], v[192:195], v[36:39]
	v_mfma_f32_16x16x32_f16 v[40:43], v[136:139], v[192:195], v[40:43]
	v_mfma_f32_16x16x32_f16 v[44:47], v[140:143], v[192:195], v[44:47]
	v_mfma_f32_16x16x32_f16 v[48:51], v[144:147], v[192:195], v[48:51]
	v_mfma_f32_16x16x32_f16 v[52:55], v[132:135], v[196:199], v[52:55]
	v_mfma_f32_16x16x32_f16 v[56:59], v[136:139], v[196:199], v[56:59]
	v_mfma_f32_16x16x32_f16 v[60:63], v[140:143], v[196:199], v[60:63]
	v_mfma_f32_16x16x32_f16 v[64:67], v[144:147], v[196:199], v[64:67]
	s_waitcnt vmcnt(8) lgkmcnt(0)
	s_barrier
	s_add_i32 s34, s32, 0x8000
	s_cmp_lg_u32 s32, 0x18000
	s_cselect_b32 s34, s34, 0
	v_add_u32_e32 v168, s34, v165
	v_add_u32_e32 v169, s34, v164
	s_add_u32 vcc_lo, s31, s32
	v_mfma_f32_16x16x32_f16 v[68:71], v[132:135], v[238:241], v[68:71]
	ds_read_b128 v[148:151], v168 offset:16
	ds_read_b128 v[184:187], v169 offset:16
	v_mfma_f32_16x16x32_f16 v[72:75], v[136:139], v[238:241], v[72:75]
	ds_read_b128 v[152:155], v168 offset:1040
	ds_read_b128 v[188:191], v169 offset:1040
	v_mfma_f32_16x16x32_f16 v[76:79], v[140:143], v[238:241], v[76:79]
	ds_read_b128 v[156:159], v168 offset:2064
	ds_read_b128 v[192:195], v169 offset:2064
	v_mfma_f32_16x16x32_f16 v[80:83], v[144:147], v[238:241], v[80:83]
	ds_read_b128 v[160:163], v168 offset:3088
	ds_read_b128 v[196:199], v169 offset:3088
	v_mfma_f32_16x16x32_f16 v[84:87], v[132:135], v[242:245], v[84:87]
	v_mfma_f32_16x16x32_f16 v[88:91], v[136:139], v[242:245], v[88:91]
	v_mfma_f32_16x16x32_f16 v[92:95], v[140:143], v[242:245], v[92:95]
	v_mfma_f32_16x16x32_f16 v[96:99], v[144:147], v[242:245], v[96:99]
	v_mfma_f32_16x16x32_f16 v[100:103], v[132:135], v[246:249], v[100:103]
	s_mov_b32 m0, vcc_lo
	s_nop 0
	global_load_lds_dwordx4 v170, s[36:37]
	v_mfma_f32_16x16x32_f16 v[104:107], v[136:139], v[246:249], v[104:107]
	s_add_u32 m0, vcc_lo, 0x400
	s_nop 0
	global_load_lds_dwordx4 v171, s[36:37]
	v_mfma_f32_16x16x32_f16 v[108:111], v[140:143], v[246:249], v[108:111]
	s_add_u32 m0, vcc_lo, 0x4000
	s_nop 0
	global_load_lds_dwordx4 v170, s[52:53]
	v_mfma_f32_16x16x32_f16 v[112:115], v[144:147], v[246:249], v[112:115]
	s_add_u32 m0, vcc_lo, 0x4400
	s_nop 0
	global_load_lds_dwordx4 v171, s[52:53]
	v_mfma_f32_16x16x32_f16 v[116:119], v[132:135], v[250:253], v[116:119]
	v_mfma_f32_16x16x32_f16 v[120:123], v[136:139], v[250:253], v[120:123]
	v_mfma_f32_16x16x32_f16 v[124:127], v[140:143], v[250:253], v[124:127]
	v_mfma_f32_16x16x32_f16 v[128:131], v[144:147], v[250:253], v[128:131]
	s_waitcnt lgkmcnt(0)
	s_mov_b32 s32, s34
	s_add_u32 s36, s36, 64
	s_addc_u32 s37, s37, 0
	s_add_u32 s52, s52, 64
	s_addc_u32 s53, s53, 0
	v_add_u32_e32 v169, s32, v164
	v_mfma_f32_16x16x32_f16 v[4:7], v[148:151], v[184:187], v[4:7]
	ds_read_b128 v[238:241], v169 offset:4112
	v_mfma_f32_16x16x32_f16 v[8:11], v[152:155], v[184:187], v[8:11]
	ds_read_b128 v[242:245], v169 offset:5136
	v_mfma_f32_16x16x32_f16 v[12:15], v[156:159], v[184:187], v[12:15]
	ds_read_b128 v[246:249], v169 offset:6160
	v_mfma_f32_16x16x32_f16 v[16:19], v[160:163], v[184:187], v[16:19]
	ds_read_b128 v[250:253], v169 offset:7184
	v_mfma_f32_16x16x32_f16 v[20:23], v[148:151], v[188:191], v[20:23]
	v_mfma_f32_16x16x32_f16 v[24:27], v[152:155], v[188:191], v[24:27]
	v_mfma_f32_16x16x32_f16 v[28:31], v[156:159], v[188:191], v[28:31]
	v_mfma_f32_16x16x32_f16 v[32:35], v[160:163], v[188:191], v[32:35]
	v_mfma_f32_16x16x32_f16 v[36:39], v[148:151], v[192:195], v[36:39]
	v_mfma_f32_16x16x32_f16 v[40:43], v[152:155], v[192:195], v[40:43]
	v_mfma_f32_16x16x32_f16 v[44:47], v[156:159], v[192:195], v[44:47]
	v_mfma_f32_16x16x32_f16 v[48:51], v[160:163], v[192:195], v[48:51]
	v_mfma_f32_16x16x32_f16 v[52:55], v[148:151], v[196:199], v[52:55]
	v_mfma_f32_16x16x32_f16 v[56:59], v[152:155], v[196:199], v[56:59]
	v_mfma_f32_16x16x32_f16 v[60:63], v[156:159], v[196:199], v[60:63]
	v_mfma_f32_16x16x32_f16 v[64:67], v[160:163], v[196:199], v[64:67]
	s_waitcnt vmcnt(8) lgkmcnt(0)
	s_barrier
	s_add_i32 s34, s32, 0x8000
	s_cmp_lg_u32 s32, 0x18000
	s_cselect_b32 s34, s34, 0
	v_add_u32_e32 v168, s34, v165
	v_add_u32_e32 v169, s34, v164
	s_add_u32 vcc_lo, s31, s32
	v_mfma_f32_16x16x32_f16 v[68:71], v[148:151], v[238:241], v[68:71]
	ds_read_b128 v[132:135], v168 offset:16
	ds_read_b128 v[184:187], v169 offset:16
	v_mfma_f32_16x16x32_f16 v[72:75], v[152:155], v[238:241], v[72:75]
	ds_read_b128 v[136:139], v168 offset:1040
	ds_read_b128 v[188:191], v169 offset:1040
	v_mfma_f32_16x16x32_f16 v[76:79], v[156:159], v[238:241], v[76:79]
	ds_read_b128 v[140:143], v168 offset:2064
	ds_read_b128 v[192:195], v169 offset:2064
	v_mfma_f32_16x16x32_f16 v[80:83], v[160:163], v[238:241], v[80:83]
	ds_read_b128 v[144:147], v168 offset:3088
	ds_read_b128 v[196:199], v169 offset:3088
	v_mfma_f32_16x16x32_f16 v[84:87], v[148:151], v[242:245], v[84:87]
	v_mfma_f32_16x16x32_f16 v[88:91], v[152:155], v[242:245], v[88:91]
	v_mfma_f32_16x16x32_f16 v[92:95], v[156:159], v[242:245], v[92:95]
	v_mfma_f32_16x16x32_f16 v[96:99], v[160:163], v[242:245], v[96:99]
	v_mfma_f32_16x16x32_f16 v[100:103], v[148:151], v[246:249], v[100:103]
	s_mov_b32 m0, vcc_lo
	s_nop 0
	global_load_lds_dwordx4 v170, s[36:37]
	v_mfma_f32_16x16x32_f16 v[104:107], v[152:155], v[246:249], v[104:107]
	s_add_u32 m0, vcc_lo, 0x400
	s_nop 0
	global_load_lds_dwordx4 v171, s[36:37]
	v_mfma_f32_16x16x32_f16 v[108:111], v[156:159], v[246:249], v[108:111]
	s_add_u32 m0, vcc_lo, 0x4000
	s_nop 0
	global_load_lds_dwordx4 v170, s[52:53]
	v_mfma_f32_16x16x32_f16 v[112:115], v[160:163], v[246:249], v[112:115]
	s_add_u32 m0, vcc_lo, 0x4400
	s_nop 0
	global_load_lds_dwordx4 v171, s[52:53]
	v_mfma_f32_16x16x32_f16 v[116:119], v[148:151], v[250:253], v[116:119]
	v_mfma_f32_16x16x32_f16 v[120:123], v[152:155], v[250:253], v[120:123]
	v_mfma_f32_16x16x32_f16 v[124:127], v[156:159], v[250:253], v[124:127]
	v_mfma_f32_16x16x32_f16 v[128:131], v[160:163], v[250:253], v[128:131]
	s_waitcnt lgkmcnt(0)
	s_mov_b32 s32, s34
	s_add_u32 s36, s36, 64
	s_addc_u32 s37, s37, 0
	s_add_u32 s52, s52, 64
	s_addc_u32 s53, s53, 0
	s_add_i32 s65, s65, 2
	s_cmp_lt_u32 s65, 124
	s_cbranch_scc1 .Lt_mlp2b
	v_add_u32_e32 v169, s32, v164
	v_mfma_f32_16x16x32_f16 v[4:7], v[132:135], v[184:187], v[4:7]
	ds_read_b128 v[238:241], v169 offset:4112
	v_mfma_f32_16x16x32_f16 v[8:11], v[136:139], v[184:187], v[8:11]
	ds_read_b128 v[242:245], v169 offset:5136
	v_mfma_f32_16x16x32_f16 v[12:15], v[140:143], v[184:187], v[12:15]
	ds_read_b128 v[246:249], v169 offset:6160
	v_mfma_f32_16x16x32_f16 v[16:19], v[144:147], v[184:187], v[16:19]
	ds_read_b128 v[250:253], v169 offset:7184
	v_mfma_f32_16x16x32_f16 v[20:23], v[132:135], v[188:191], v[20:23]
	v_mfma_f32_16x16x32_f16 v[24:27], v[136:139], v[188:191], v[24:27]
	v_mfma_f32_16x16x32_f16 v[28:31], v[140:143], v[188:191], v[28:31]
	v_mfma_f32_16x16x32_f16 v[32:35], v[144:147], v[188:191], v[32:35]
	v_mfma_f32_16x16x32_f16 v[36:39], v[132:135], v[192:195], v[36:39]
	v_mfma_f32_16x16x32_f16 v[40:43], v[136:139], v[192:195], v[40:43]
	v_mfma_f32_16x16x32_f16 v[44:47], v[140:143], v[192:195], v[44:47]
	v_mfma_f32_16x16x32_f16 v[48:51], v[144:147], v[192:195], v[48:51]
	v_mfma_f32_16x16x32_f16 v[52:55], v[132:135], v[196:199], v[52:55]
	v_mfma_f32_16x16x32_f16 v[56:59], v[136:139], v[196:199], v[56:59]
	v_mfma_f32_16x16x32_f16 v[60:63], v[140:143], v[196:199], v[60:63]
	v_mfma_f32_16x16x32_f16 v[64:67], v[144:147], v[196:199], v[64:67]
	s_waitcnt vmcnt(8) lgkmcnt(0)
	s_barrier
	s_add_i32 s34, s32, 0x8000
	s_cmp_lg_u32 s32, 0x18000
	s_cselect_b32 s34, s34, 0
	v_add_u32_e32 v168, s34, v165
	v_add_u32_e32 v169, s34, v164
	v_mfma_f32_16x16x32_f16 v[68:71], v[132:135], v[238:241], v[68:71]
	ds_read_b128 v[148:151], v168 offset:16
	ds_read_b128 v[184:187], v169 offset:16
	v_mfma_f32_16x16x32_f16 v[72:75], v[136:139], v[238:241], v[72:75]
	ds_read_b128 v[152:155], v168 offset:1040
	ds_read_b128 v[188:191], v169 offset:1040
	v_mfma_f32_16x16x32_f16 v[76:79], v[140:143], v[238:241], v[76:79]
	ds_read_b128 v[156:159], v168 offset:2064
	ds_read_b128 v[192:195], v169 offset:2064
	v_mfma_f32_16x16x32_f16 v[80:83], v[144:147], v[238:241], v[80:83]
	ds_read_b128 v[160:163], v168 offset:3088
	ds_read_b128 v[196:199], v169 offset:3088
	v_mfma_f32_16x16x32_f16 v[84:87], v[132:135], v[242:245], v[84:87]
	v_mfma_f32_16x16x32_f16 v[88:91], v[136:139], v[242:245], v[88:91]
	v_mfma_f32_16x16x32_f16 v[92:95], v[140:143], v[242:245], v[92:95]
	v_mfma_f32_16x16x32_f16 v[96:99], v[144:147], v[242:245], v[96:99]
	v_mfma_f32_16x16x32_f16 v[100:103], v[132:135], v[246:249], v[100:103]
	v_mfma_f32_16x16x32_f16 v[104:107], v[136:139], v[246:249], v[104:107]
	v_mfma_f32_16x16x32_f16 v[108:111], v[140:143], v[246:249], v[108:111]
	v_mfma_f32_16x16x32_f16 v[112:115], v[144:147], v[246:249], v[112:115]
	v_mfma_f32_16x16x32_f16 v[116:119], v[132:135], v[250:253], v[116:119]
	v_mfma_f32_16x16x32_f16 v[120:123], v[136:139], v[250:253], v[120:123]
	v_mfma_f32_16x16x32_f16 v[124:127], v[140:143], v[250:253], v[124:127]
	v_mfma_f32_16x16x32_f16 v[128:131], v[144:147], v[250:253], v[128:131]
	s_waitcnt lgkmcnt(0)
	s_mov_b32 s32, s34
	v_add_u32_e32 v169, s32, v164
	v_mfma_f32_16x16x32_f16 v[4:7], v[148:151], v[184:187], v[4:7]
	ds_read_b128 v[238:241], v169 offset:4112
	v_mfma_f32_16x16x32_f16 v[8:11], v[152:155], v[184:187], v[8:11]
	ds_read_b128 v[242:245], v169 offset:5136
	v_mfma_f32_16x16x32_f16 v[12:15], v[156:159], v[184:187], v[12:15]
	ds_read_b128 v[246:249], v169 offset:6160
	v_mfma_f32_16x16x32_f16 v[16:19], v[160:163], v[184:187], v[16:19]
	ds_read_b128 v[250:253], v169 offset:7184
	v_mfma_f32_16x16x32_f16 v[20:23], v[148:151], v[188:191], v[20:23]
	v_mfma_f32_16x16x32_f16 v[24:27], v[152:155], v[188:191], v[24:27]
	v_mfma_f32_16x16x32_f16 v[28:31], v[156:159], v[188:191], v[28:31]
	v_mfma_f32_16x16x32_f16 v[32:35], v[160:163], v[188:191], v[32:35]
	v_mfma_f32_16x16x32_f16 v[36:39], v[148:151], v[192:195], v[36:39]
	v_mfma_f32_16x16x32_f16 v[40:43], v[152:155], v[192:195], v[40:43]
	v_mfma_f32_16x16x32_f16 v[44:47], v[156:159], v[192:195], v[44:47]
	v_mfma_f32_16x16x32_f16 v[48:51], v[160:163], v[192:195], v[48:51]
	v_mfma_f32_16x16x32_f16 v[52:55], v[148:151], v[196:199], v[52:55]
	v_mfma_f32_16x16x32_f16 v[56:59], v[152:155], v[196:199], v[56:59]
	v_mfma_f32_16x16x32_f16 v[60:63], v[156:159], v[196:199], v[60:63]
	v_mfma_f32_16x16x32_f16 v[64:67], v[160:163], v[196:199], v[64:67]
	s_waitcnt vmcnt(4) lgkmcnt(0)
	s_barrier
	s_add_i32 s34, s32, 0x8000
	s_cmp_lg_u32 s32, 0x18000
	s_cselect_b32 s34, s34, 0
	v_add_u32_e32 v168, s34, v165
	v_add_u32_e32 v169, s34, v164
	v_mfma_f32_16x16x32_f16 v[68:71], v[148:151], v[238:241], v[68:71]
	ds_read_b128 v[132:135], v168 offset:16
	ds_read_b128 v[184:187], v169 offset:16
	v_mfma_f32_16x16x32_f16 v[72:75], v[152:155], v[238:241], v[72:75]
	ds_read_b128 v[136:139], v168 offset:1040
	ds_read_b128 v[188:191], v169 offset:1040
	v_mfma_f32_16x16x32_f16 v[76:79], v[156:159], v[238:241], v[76:79]
	ds_read_b128 v[140:143], v168 offset:2064
	ds_read_b128 v[192:195], v169 offset:2064
	v_mfma_f32_16x16x32_f16 v[80:83], v[160:163], v[238:241], v[80:83]
	ds_read_b128 v[144:147], v168 offset:3088
	ds_read_b128 v[196:199], v169 offset:3088
	v_mfma_f32_16x16x32_f16 v[84:87], v[148:151], v[242:245], v[84:87]
	v_mfma_f32_16x16x32_f16 v[88:91], v[152:155], v[242:245], v[88:91]
	v_mfma_f32_16x16x32_f16 v[92:95], v[156:159], v[242:245], v[92:95]
	v_mfma_f32_16x16x32_f16 v[96:99], v[160:163], v[242:245], v[96:99]
	v_mfma_f32_16x16x32_f16 v[100:103], v[148:151], v[246:249], v[100:103]
	v_mfma_f32_16x16x32_f16 v[104:107], v[152:155], v[246:249], v[104:107]
	v_mfma_f32_16x16x32_f16 v[108:111], v[156:159], v[246:249], v[108:111]
	v_mfma_f32_16x16x32_f16 v[112:115], v[160:163], v[246:249], v[112:115]
	v_mfma_f32_16x16x32_f16 v[116:119], v[148:151], v[250:253], v[116:119]
	v_mfma_f32_16x16x32_f16 v[120:123], v[152:155], v[250:253], v[120:123]
	v_mfma_f32_16x16x32_f16 v[124:127], v[156:159], v[250:253], v[124:127]
	v_mfma_f32_16x16x32_f16 v[128:131], v[160:163], v[250:253], v[128:131]
	s_waitcnt lgkmcnt(0)
	s_mov_b32 s32, s34
	v_add_u32_e32 v169, s32, v164
	v_mfma_f32_16x16x32_f16 v[4:7], v[132:135], v[184:187], v[4:7]
	ds_read_b128 v[238:241], v169 offset:4112
	v_mfma_f32_16x16x32_f16 v[8:11], v[136:139], v[184:187], v[8:11]
	ds_read_b128 v[242:245], v169 offset:5136
	v_mfma_f32_16x16x32_f16 v[12:15], v[140:143], v[184:187], v[12:15]
	ds_read_b128 v[246:249], v169 offset:6160
	v_mfma_f32_16x16x32_f16 v[16:19], v[144:147], v[184:187], v[16:19]
	ds_read_b128 v[250:253], v169 offset:7184
	v_mfma_f32_16x16x32_f16 v[20:23], v[132:135], v[188:191], v[20:23]
	v_mfma_f32_16x16x32_f16 v[24:27], v[136:139], v[188:191], v[24:27]
	v_mfma_f32_16x16x32_f16 v[28:31], v[140:143], v[188:191], v[28:31]
	v_mfma_f32_16x16x32_f16 v[32:35], v[144:147], v[188:191], v[32:35]
	v_mfma_f32_16x16x32_f16 v[36:39], v[132:135], v[192:195], v[36:39]
	v_mfma_f32_16x16x32_f16 v[40:43], v[136:139], v[192:195], v[40:43]
	v_mfma_f32_16x16x32_f16 v[44:47], v[140:143], v[192:195], v[44:47]
	v_mfma_f32_16x16x32_f16 v[48:51], v[144:147], v[192:195], v[48:51]
	v_mfma_f32_16x16x32_f16 v[52:55], v[132:135], v[196:199], v[52:55]
	v_mfma_f32_16x16x32_f16 v[56:59], v[136:139], v[196:199], v[56:59]
	v_mfma_f32_16x16x32_f16 v[60:63], v[140:143], v[196:199], v[60:63]
	v_mfma_f32_16x16x32_f16 v[64:67], v[144:147], v[196:199], v[64:67]
	s_waitcnt vmcnt(0) lgkmcnt(0)
	s_barrier
	s_add_i32 s34, s32, 0x8000
	s_cmp_lg_u32 s32, 0x18000
	s_cselect_b32 s34, s34, 0
	v_add_u32_e32 v168, s34, v165
	v_add_u32_e32 v169, s34, v164
	v_mfma_f32_16x16x32_f16 v[68:71], v[132:135], v[238:241], v[68:71]
	ds_read_b128 v[148:151], v168 offset:16
	ds_read_b128 v[184:187], v169 offset:16
	v_mfma_f32_16x16x32_f16 v[72:75], v[136:139], v[238:241], v[72:75]
	ds_read_b128 v[152:155], v168 offset:1040
	ds_read_b128 v[188:191], v169 offset:1040
	v_mfma_f32_16x16x32_f16 v[76:79], v[140:143], v[238:241], v[76:79]
	ds_read_b128 v[156:159], v168 offset:2064
	ds_read_b128 v[192:195], v169 offset:2064
	v_mfma_f32_16x16x32_f16 v[80:83], v[144:147], v[238:241], v[80:83]
	ds_read_b128 v[160:163], v168 offset:3088
	ds_read_b128 v[196:199], v169 offset:3088
	v_mfma_f32_16x16x32_f16 v[84:87], v[132:135], v[242:245], v[84:87]
	v_mfma_f32_16x16x32_f16 v[88:91], v[136:139], v[242:245], v[88:91]
	v_mfma_f32_16x16x32_f16 v[92:95], v[140:143], v[242:245], v[92:95]
	v_mfma_f32_16x16x32_f16 v[96:99], v[144:147], v[242:245], v[96:99]
	v_mfma_f32_16x16x32_f16 v[100:103], v[132:135], v[246:249], v[100:103]
	v_mfma_f32_16x16x32_f16 v[104:107], v[136:139], v[246:249], v[104:107]
	v_mfma_f32_16x16x32_f16 v[108:111], v[140:143], v[246:249], v[108:111]
	v_mfma_f32_16x16x32_f16 v[112:115], v[144:147], v[246:249], v[112:115]
	v_mfma_f32_16x16x32_f16 v[116:119], v[132:135], v[250:253], v[116:119]
	v_mfma_f32_16x16x32_f16 v[120:123], v[136:139], v[250:253], v[120:123]
	v_mfma_f32_16x16x32_f16 v[124:127], v[140:143], v[250:253], v[124:127]
	v_mfma_f32_16x16x32_f16 v[128:131], v[144:147], v[250:253], v[128:131]
	s_waitcnt lgkmcnt(0)
	s_mov_b32 s32, s34
	v_add_u32_e32 v169, s32, v164
	v_mfma_f32_16x16x32_f16 v[4:7], v[148:151], v[184:187], v[4:7]
	ds_read_b128 v[238:241], v169 offset:4112
	v_mfma_f32_16x16x32_f16 v[8:11], v[152:155], v[184:187], v[8:11]
	ds_read_b128 v[242:245], v169 offset:5136
	v_mfma_f32_16x16x32_f16 v[12:15], v[156:159], v[184:187], v[12:15]
	ds_read_b128 v[246:249], v169 offset:6160
	v_mfma_f32_16x16x32_f16 v[16:19], v[160:163], v[184:187], v[16:19]
	ds_read_b128 v[250:253], v169 offset:7184
	v_mfma_f32_16x16x32_f16 v[20:23], v[148:151], v[188:191], v[20:23]
	v_mfma_f32_16x16x32_f16 v[24:27], v[152:155], v[188:191], v[24:27]
	v_mfma_f32_16x16x32_f16 v[28:31], v[156:159], v[188:191], v[28:31]
	v_mfma_f32_16x16x32_f16 v[32:35], v[160:163], v[188:191], v[32:35]
	v_mfma_f32_16x16x32_f16 v[36:39], v[148:151], v[192:195], v[36:39]
	v_mfma_f32_16x16x32_f16 v[40:43], v[152:155], v[192:195], v[40:43]
	v_mfma_f32_16x16x32_f16 v[44:47], v[156:159], v[192:195], v[44:47]
	v_mfma_f32_16x16x32_f16 v[48:51], v[160:163], v[192:195], v[48:51]
	v_mfma_f32_16x16x32_f16 v[52:55], v[148:151], v[196:199], v[52:55]
	v_mfma_f32_16x16x32_f16 v[56:59], v[152:155], v[196:199], v[56:59]
	v_mfma_f32_16x16x32_f16 v[60:63], v[156:159], v[196:199], v[60:63]
	v_mfma_f32_16x16x32_f16 v[64:67], v[160:163], v[196:199], v[64:67]
	s_waitcnt lgkmcnt(0)
	s_barrier
	v_mfma_f32_16x16x32_f16 v[68:71], v[148:151], v[238:241], v[68:71]
	v_mfma_f32_16x16x32_f16 v[72:75], v[152:155], v[238:241], v[72:75]
	v_mfma_f32_16x16x32_f16 v[76:79], v[156:159], v[238:241], v[76:79]
	v_mfma_f32_16x16x32_f16 v[80:83], v[160:163], v[238:241], v[80:83]
	v_mfma_f32_16x16x32_f16 v[84:87], v[148:151], v[242:245], v[84:87]
	v_mfma_f32_16x16x32_f16 v[88:91], v[152:155], v[242:245], v[88:91]
	v_mfma_f32_16x16x32_f16 v[92:95], v[156:159], v[242:245], v[92:95]
	v_mfma_f32_16x16x32_f16 v[96:99], v[160:163], v[242:245], v[96:99]
	v_mfma_f32_16x16x32_f16 v[100:103], v[148:151], v[246:249], v[100:103]
	v_mfma_f32_16x16x32_f16 v[104:107], v[152:155], v[246:249], v[104:107]
	v_mfma_f32_16x16x32_f16 v[108:111], v[156:159], v[246:249], v[108:111]
	v_mfma_f32_16x16x32_f16 v[112:115], v[160:163], v[246:249], v[112:115]
	v_mfma_f32_16x16x32_f16 v[116:119], v[148:151], v[250:253], v[116:119]
	v_mfma_f32_16x16x32_f16 v[120:123], v[152:155], v[250:253], v[120:123]
	v_mfma_f32_16x16x32_f16 v[124:127], v[156:159], v[250:253], v[124:127]
	v_mfma_f32_16x16x32_f16 v[128:131], v[160:163], v[250:253], v[128:131]
	s_sub_u32 s77, s35, 0x1000
	s_lshr_b32 s77, s77, 12
	s_add_u32 s77, s77, 1
	s_cmp_lt_u32 s35, 0x1000
	s_cselect_b32 s77, 0, s77
	s_mul_i32 s77, s77, 0x6000
	s_add_u32 s68, s46, s77
	s_addc_u32 s69, s47, 0
	s_add_u32 s68, s68, 0xfa2e600
	s_addc_u32 s69, s69, 0
	s_lshl_b32 s82, s35, 11
	s_add_u32 s80, s48, s82
	s_addc_u32 s81, s49, 0
	s_lshl_b32 s82, s30, 1
	s_add_u32 s80, s80, s82
	s_addc_u32 s81, s81, 0
	v_and_b32_e32 v172, 15, v200
	v_bfe_u32 v173, v200, 4, 2
	v_bfe_u32 v174, v200, 6, 2
	v_bfe_u32 v175, v200, 8, 1
	v_lshlrev_b32_e32 v176, 6, v174
	v_lshl_or_b32 v176, v173, 2, v176
	v_lshl_or_b32 v175, v175, 7, v172
	v_lshlrev_b32_e32 v175, 11, v175
	v_lshl_add_u32 v177, v176, 1, v175
	v_add_u32_e32 v176, s30, v176
	v_lshlrev_b32_e32 v176, 2, v176
	global_load_dwordx4 v[132:135], v176, s[68:69]
	global_load_dwordx4 v[136:139], v176, s[68:69] offset:64
	global_load_dwordx4 v[140:143], v176, s[68:69] offset:128
	global_load_dwordx4 v[144:147], v176, s[68:69] offset:192
	v_and_b32_e32 v172, 1, v173
	v_mul_u32_u24_e32 v172, 24, v172
	v_add_u32_e32 v177, v177, v172
	v_mov_b32_e32 v178, v177
	global_load_dwordx4 v[184:187], v178, s[80:81]
	global_load_dwordx4 v[188:191], v178, s[80:81] offset:64
	v_add_u32_e32 v178, 0x8000, v178
	global_load_dwordx4 v[238:241], v178, s[80:81]
	global_load_dwordx4 v[242:245], v178, s[80:81] offset:64
	s_waitcnt vmcnt(3)
	v_permlane16_swap_b32_e32 v184, v186
	v_permlane16_swap_b32_e32 v185, v187
	v_cvt_f32_f16_e32 v164, v184
	v_cvt_f32_f16_sdwa v165, v184 dst_sel:DWORD dst_unused:UNUSED_PAD src0_sel:WORD_1
	v_cvt_f32_f16_e32 v166, v185
	v_cvt_f32_f16_sdwa v167, v185 dst_sel:DWORD dst_unused:UNUSED_PAD src0_sel:WORD_1
	v_pk_mul_f32 v[164:165], v[164:165], s[84:85] op_sel_hi:[1,0]
	v_pk_mul_f32 v[166:167], v[166:167], s[84:85] op_sel_hi:[1,0]
	v_pk_fma_f32 v[4:5], v[4:5], v[132:133], v[164:165]
	v_pk_fma_f32 v[6:7], v[6:7], v[134:135], v[166:167]
	v_cvt_pk_f16_f32 v172, v4, v5
	v_cvt_pk_f16_f32 v173, v6, v7
	v_cvt_f32_f16_e32 v164, v186
	v_cvt_f32_f16_sdwa v165, v186 dst_sel:DWORD dst_unused:UNUSED_PAD src0_sel:WORD_1
	v_cvt_f32_f16_e32 v166, v187
	v_cvt_f32_f16_sdwa v167, v187 dst_sel:DWORD dst_unused:UNUSED_PAD src0_sel:WORD_1
	v_pk_mul_f32 v[164:165], v[164:165], s[84:85] op_sel_hi:[1,0]
	v_pk_mul_f32 v[166:167], v[166:167], s[84:85] op_sel_hi:[1,0]
	v_pk_fma_f32 v[8:9], v[8:9], v[136:137], v[164:165]
	v_pk_fma_f32 v[10:11], v[10:11], v[138:139], v[166:167]
	v_cvt_pk_f16_f32 v174, v8, v9
	v_cvt_pk_f16_f32 v175, v10, v11
	s_nop 1
	v_permlane16_swap_b32_e32 v172, v174
	v_permlane16_swap_b32_e32 v173, v175
	global_store_dwordx4 v177, v[172:175], s[80:81]
	s_waitcnt vmcnt(3)
	v_permlane16_swap_b32_e32 v188, v190
	v_permlane16_swap_b32_e32 v189, v191
	v_cvt_f32_f16_e32 v164, v188
	v_cvt_f32_f16_sdwa v165, v188 dst_sel:DWORD dst_unused:UNUSED_PAD src0_sel:WORD_1
	v_cvt_f32_f16_e32 v166, v189
	v_cvt_f32_f16_sdwa v167, v189 dst_sel:DWORD dst_unused:UNUSED_PAD src0_sel:WORD_1
	v_pk_mul_f32 v[164:165], v[164:165], s[84:85] op_sel_hi:[1,0]
	v_pk_mul_f32 v[166:167], v[166:167], s[84:85] op_sel_hi:[1,0]
	v_pk_fma_f32 v[12:13], v[12:13], v[140:141], v[164:165]
	v_pk_fma_f32 v[14:15], v[14:15], v[142:143], v[166:167]
	v_cvt_pk_f16_f32 v228, v12, v13
	v_cvt_pk_f16_f32 v229, v14, v15
	v_cvt_f32_f16_e32 v164, v190
	v_cvt_f32_f16_sdwa v165, v190 dst_sel:DWORD dst_unused:UNUSED_PAD src0_sel:WORD_1
	v_cvt_f32_f16_e32 v166, v191
	v_cvt_f32_f16_sdwa v167, v191 dst_sel:DWORD dst_unused:UNUSED_PAD src0_sel:WORD_1
	v_pk_mul_f32 v[164:165], v[164:165], s[84:85] op_sel_hi:[1,0]
	v_pk_mul_f32 v[166:167], v[166:167], s[84:85] op_sel_hi:[1,0]
	v_pk_fma_f32 v[16:17], v[16:17], v[144:145], v[164:165]
	v_pk_fma_f32 v[18:19], v[18:19], v[146:147], v[166:167]
	v_cvt_pk_f16_f32 v230, v16, v17
	v_cvt_pk_f16_f32 v231, v18, v19
	s_nop 1
	v_permlane16_swap_b32_e32 v228, v230
	v_permlane16_swap_b32_e32 v229, v231
	global_store_dwordx4 v177, v[228:231], s[80:81] offset:64
	v_add_u32_e32 v177, 0x8000, v177
	v_add_u32_e32 v178, 0x8000, v178
	global_load_dwordx4 v[184:187], v178, s[80:81]
	global_load_dwordx4 v[188:191], v178, s[80:81] offset:64
	s_waitcnt vmcnt(5)
	v_permlane16_swap_b32_e32 v238, v240
	v_permlane16_swap_b32_e32 v239, v241
	v_cvt_f32_f16_e32 v164, v238
	v_cvt_f32_f16_sdwa v165, v238 dst_sel:DWORD dst_unused:UNUSED_PAD src0_sel:WORD_1
	v_cvt_f32_f16_e32 v166, v239
	v_cvt_f32_f16_sdwa v167, v239 dst_sel:DWORD dst_unused:UNUSED_PAD src0_sel:WORD_1
	v_pk_mul_f32 v[164:165], v[164:165], s[84:85] op_sel_hi:[1,0]
	v_pk_mul_f32 v[166:167], v[166:167], s[84:85] op_sel_hi:[1,0]
	v_pk_fma_f32 v[20:21], v[20:21], v[132:133], v[164:165]
	v_pk_fma_f32 v[22:23], v[22:23], v[134:135], v[166:167]
	v_cvt_pk_f16_f32 v172, v20, v21
	v_cvt_pk_f16_f32 v173, v22, v23
	v_cvt_f32_f16_e32 v164, v240
	v_cvt_f32_f16_sdwa v165, v240 dst_sel:DWORD dst_unused:UNUSED_PAD src0_sel:WORD_1
	v_cvt_f32_f16_e32 v166, v241
	v_cvt_f32_f16_sdwa v167, v241 dst_sel:DWORD dst_unused:UNUSED_PAD src0_sel:WORD_1
	v_pk_mul_f32 v[164:165], v[164:165], s[84:85] op_sel_hi:[1,0]
	v_pk_mul_f32 v[166:167], v[166:167], s[84:85] op_sel_hi:[1,0]
	v_pk_fma_f32 v[24:25], v[24:25], v[136:137], v[164:165]
	v_pk_fma_f32 v[26:27], v[26:27], v[138:139], v[166:167]
	v_cvt_pk_f16_f32 v174, v24, v25
	v_cvt_pk_f16_f32 v175, v26, v27
	s_nop 1
	v_permlane16_swap_b32_e32 v172, v174
	v_permlane16_swap_b32_e32 v173, v175
	global_store_dwordx4 v177, v[172:175], s[80:81]
	s_waitcnt vmcnt(5)
	v_permlane16_swap_b32_e32 v242, v244
	v_permlane16_swap_b32_e32 v243, v245
	v_cvt_f32_f16_e32 v164, v242
	v_cvt_f32_f16_sdwa v165, v242 dst_sel:DWORD dst_unused:UNUSED_PAD src0_sel:WORD_1
	v_cvt_f32_f16_e32 v166, v243
	v_cvt_f32_f16_sdwa v167, v243 dst_sel:DWORD dst_unused:UNUSED_PAD src0_sel:WORD_1
	v_pk_mul_f32 v[164:165], v[164:165], s[84:85] op_sel_hi:[1,0]
	v_pk_mul_f32 v[166:167], v[166:167], s[84:85] op_sel_hi:[1,0]
	v_pk_fma_f32 v[28:29], v[28:29], v[140:141], v[164:165]
	v_pk_fma_f32 v[30:31], v[30:31], v[142:143], v[166:167]
	v_cvt_pk_f16_f32 v228, v28, v29
	v_cvt_pk_f16_f32 v229, v30, v31
	v_cvt_f32_f16_e32 v164, v244
	v_cvt_f32_f16_sdwa v165, v244 dst_sel:DWORD dst_unused:UNUSED_PAD src0_sel:WORD_1
	v_cvt_f32_f16_e32 v166, v245
	v_cvt_f32_f16_sdwa v167, v245 dst_sel:DWORD dst_unused:UNUSED_PAD src0_sel:WORD_1
	v_pk_mul_f32 v[164:165], v[164:165], s[84:85] op_sel_hi:[1,0]
	v_pk_mul_f32 v[166:167], v[166:167], s[84:85] op_sel_hi:[1,0]
	v_pk_fma_f32 v[32:33], v[32:33], v[144:145], v[164:165]
	v_pk_fma_f32 v[34:35], v[34:35], v[146:147], v[166:167]
	v_cvt_pk_f16_f32 v230, v32, v33
	v_cvt_pk_f16_f32 v231, v34, v35
	s_nop 1
	v_permlane16_swap_b32_e32 v228, v230
	v_permlane16_swap_b32_e32 v229, v231
	global_store_dwordx4 v177, v[228:231], s[80:81] offset:64
	v_add_u32_e32 v177, 0x8000, v177
	v_add_u32_e32 v178, 0x8000, v178
	global_load_dwordx4 v[238:241], v178, s[80:81]
	global_load_dwordx4 v[242:245], v178, s[80:81] offset:64
	s_waitcnt vmcnt(5)
	v_permlane16_swap_b32_e32 v184, v186
	v_permlane16_swap_b32_e32 v185, v187
	v_cvt_f32_f16_e32 v164, v184
	v_cvt_f32_f16_sdwa v165, v184 dst_sel:DWORD dst_unused:UNUSED_PAD src0_sel:WORD_1
	v_cvt_f32_f16_e32 v166, v185
	v_cvt_f32_f16_sdwa v167, v185 dst_sel:DWORD dst_unused:UNUSED_PAD src0_sel:WORD_1
	v_pk_mul_f32 v[164:165], v[164:165], s[84:85] op_sel_hi:[1,0]
	v_pk_mul_f32 v[166:167], v[166:167], s[84:85] op_sel_hi:[1,0]
	v_pk_fma_f32 v[36:37], v[36:37], v[132:133], v[164:165]
	v_pk_fma_f32 v[38:39], v[38:39], v[134:135], v[166:167]
	v_cvt_pk_f16_f32 v172, v36, v37
	v_cvt_pk_f16_f32 v173, v38, v39
	v_cvt_f32_f16_e32 v164, v186
	v_cvt_f32_f16_sdwa v165, v186 dst_sel:DWORD dst_unused:UNUSED_PAD src0_sel:WORD_1
	v_cvt_f32_f16_e32 v166, v187
	v_cvt_f32_f16_sdwa v167, v187 dst_sel:DWORD dst_unused:UNUSED_PAD src0_sel:WORD_1
	v_pk_mul_f32 v[164:165], v[164:165], s[84:85] op_sel_hi:[1,0]
	v_pk_mul_f32 v[166:167], v[166:167], s[84:85] op_sel_hi:[1,0]
	v_pk_fma_f32 v[40:41], v[40:41], v[136:137], v[164:165]
	v_pk_fma_f32 v[42:43], v[42:43], v[138:139], v[166:167]
	v_cvt_pk_f16_f32 v174, v40, v41
	v_cvt_pk_f16_f32 v175, v42, v43
	s_nop 1
	v_permlane16_swap_b32_e32 v172, v174
	v_permlane16_swap_b32_e32 v173, v175
	global_store_dwordx4 v177, v[172:175], s[80:81]
	s_waitcnt vmcnt(5)
	v_permlane16_swap_b32_e32 v188, v190
	v_permlane16_swap_b32_e32 v189, v191
	v_cvt_f32_f16_e32 v164, v188
	v_cvt_f32_f16_sdwa v165, v188 dst_sel:DWORD dst_unused:UNUSED_PAD src0_sel:WORD_1
	v_cvt_f32_f16_e32 v166, v189
	v_cvt_f32_f16_sdwa v167, v189 dst_sel:DWORD dst_unused:UNUSED_PAD src0_sel:WORD_1
	v_pk_mul_f32 v[164:165], v[164:165], s[84:85] op_sel_hi:[1,0]
	v_pk_mul_f32 v[166:167], v[166:167], s[84:85] op_sel_hi:[1,0]
	v_pk_fma_f32 v[44:45], v[44:45], v[140:141], v[164:165]
	v_pk_fma_f32 v[46:47], v[46:47], v[142:143], v[166:167]
	v_cvt_pk_f16_f32 v228, v44, v45
	v_cvt_pk_f16_f32 v229, v46, v47
	v_cvt_f32_f16_e32 v164, v190
	v_cvt_f32_f16_sdwa v165, v190 dst_sel:DWORD dst_unused:UNUSED_PAD src0_sel:WORD_1
	v_cvt_f32_f16_e32 v166, v191
	v_cvt_f32_f16_sdwa v167, v191 dst_sel:DWORD dst_unused:UNUSED_PAD src0_sel:WORD_1
	v_pk_mul_f32 v[164:165], v[164:165], s[84:85] op_sel_hi:[1,0]
	v_pk_mul_f32 v[166:167], v[166:167], s[84:85] op_sel_hi:[1,0]
	v_pk_fma_f32 v[48:49], v[48:49], v[144:145], v[164:165]
	v_pk_fma_f32 v[50:51], v[50:51], v[146:147], v[166:167]
	v_cvt_pk_f16_f32 v230, v48, v49
	v_cvt_pk_f16_f32 v231, v50, v51
	s_nop 1
	v_permlane16_swap_b32_e32 v228, v230
	v_permlane16_swap_b32_e32 v229, v231
	global_store_dwordx4 v177, v[228:231], s[80:81] offset:64
	v_add_u32_e32 v177, 0x8000, v177
	v_add_u32_e32 v178, 0x8000, v178
	global_load_dwordx4 v[184:187], v178, s[80:81]
	global_load_dwordx4 v[188:191], v178, s[80:81] offset:64
	s_waitcnt vmcnt(5)
	v_permlane16_swap_b32_e32 v238, v240
	v_permlane16_swap_b32_e32 v239, v241
	v_cvt_f32_f16_e32 v164, v238
	v_cvt_f32_f16_sdwa v165, v238 dst_sel:DWORD dst_unused:UNUSED_PAD src0_sel:WORD_1
	v_cvt_f32_f16_e32 v166, v239
	v_cvt_f32_f16_sdwa v167, v239 dst_sel:DWORD dst_unused:UNUSED_PAD src0_sel:WORD_1
	v_pk_mul_f32 v[164:165], v[164:165], s[84:85] op_sel_hi:[1,0]
	v_pk_mul_f32 v[166:167], v[166:167], s[84:85] op_sel_hi:[1,0]
	v_pk_fma_f32 v[52:53], v[52:53], v[132:133], v[164:165]
	v_pk_fma_f32 v[54:55], v[54:55], v[134:135], v[166:167]
	v_cvt_pk_f16_f32 v172, v52, v53
	v_cvt_pk_f16_f32 v173, v54, v55
	v_cvt_f32_f16_e32 v164, v240
	v_cvt_f32_f16_sdwa v165, v240 dst_sel:DWORD dst_unused:UNUSED_PAD src0_sel:WORD_1
	v_cvt_f32_f16_e32 v166, v241
	v_cvt_f32_f16_sdwa v167, v241 dst_sel:DWORD dst_unused:UNUSED_PAD src0_sel:WORD_1
	v_pk_mul_f32 v[164:165], v[164:165], s[84:85] op_sel_hi:[1,0]
	v_pk_mul_f32 v[166:167], v[166:167], s[84:85] op_sel_hi:[1,0]
	v_pk_fma_f32 v[56:57], v[56:57], v[136:137], v[164:165]
	v_pk_fma_f32 v[58:59], v[58:59], v[138:139], v[166:167]
	v_cvt_pk_f16_f32 v174, v56, v57
	v_cvt_pk_f16_f32 v175, v58, v59
	s_nop 1
	v_permlane16_swap_b32_e32 v172, v174
	v_permlane16_swap_b32_e32 v173, v175
	global_store_dwordx4 v177, v[172:175], s[80:81]
	s_waitcnt vmcnt(5)
	v_permlane16_swap_b32_e32 v242, v244
	v_permlane16_swap_b32_e32 v243, v245
	v_cvt_f32_f16_e32 v164, v242
	v_cvt_f32_f16_sdwa v165, v242 dst_sel:DWORD dst_unused:UNUSED_PAD src0_sel:WORD_1
	v_cvt_f32_f16_e32 v166, v243
	v_cvt_f32_f16_sdwa v167, v243 dst_sel:DWORD dst_unused:UNUSED_PAD src0_sel:WORD_1
	v_pk_mul_f32 v[164:165], v[164:165], s[84:85] op_sel_hi:[1,0]
	v_pk_mul_f32 v[166:167], v[166:167], s[84:85] op_sel_hi:[1,0]
	v_pk_fma_f32 v[60:61], v[60:61], v[140:141], v[164:165]
	v_pk_fma_f32 v[62:63], v[62:63], v[142:143], v[166:167]
	v_cvt_pk_f16_f32 v228, v60, v61
	v_cvt_pk_f16_f32 v229, v62, v63
	v_cvt_f32_f16_e32 v164, v244
	v_cvt_f32_f16_sdwa v165, v244 dst_sel:DWORD dst_unused:UNUSED_PAD src0_sel:WORD_1
	v_cvt_f32_f16_e32 v166, v245
	v_cvt_f32_f16_sdwa v167, v245 dst_sel:DWORD dst_unused:UNUSED_PAD src0_sel:WORD_1
	v_pk_mul_f32 v[164:165], v[164:165], s[84:85] op_sel_hi:[1,0]
	v_pk_mul_f32 v[166:167], v[166:167], s[84:85] op_sel_hi:[1,0]
	v_pk_fma_f32 v[64:65], v[64:65], v[144:145], v[164:165]
	v_pk_fma_f32 v[66:67], v[66:67], v[146:147], v[166:167]
	v_cvt_pk_f16_f32 v230, v64, v65
	v_cvt_pk_f16_f32 v231, v66, v67
	s_nop 1
	v_permlane16_swap_b32_e32 v228, v230
	v_permlane16_swap_b32_e32 v229, v231
	global_store_dwordx4 v177, v[228:231], s[80:81] offset:64
	v_add_u32_e32 v177, 0x8000, v177
	v_add_u32_e32 v178, 0x8000, v178
	global_load_dwordx4 v[238:241], v178, s[80:81]
	global_load_dwordx4 v[242:245], v178, s[80:81] offset:64
	s_waitcnt vmcnt(5)
	v_permlane16_swap_b32_e32 v184, v186
	v_permlane16_swap_b32_e32 v185, v187
	v_cvt_f32_f16_e32 v164, v184
	v_cvt_f32_f16_sdwa v165, v184 dst_sel:DWORD dst_unused:UNUSED_PAD src0_sel:WORD_1
	v_cvt_f32_f16_e32 v166, v185
	v_cvt_f32_f16_sdwa v167, v185 dst_sel:DWORD dst_unused:UNUSED_PAD src0_sel:WORD_1
	v_pk_mul_f32 v[164:165], v[164:165], s[84:85] op_sel_hi:[1,0]
	v_pk_mul_f32 v[166:167], v[166:167], s[84:85] op_sel_hi:[1,0]
	v_pk_fma_f32 v[68:69], v[68:69], v[132:133], v[164:165]
	v_pk_fma_f32 v[70:71], v[70:71], v[134:135], v[166:167]
	v_cvt_pk_f16_f32 v172, v68, v69
	v_cvt_pk_f16_f32 v173, v70, v71
	v_cvt_f32_f16_e32 v164, v186
	v_cvt_f32_f16_sdwa v165, v186 dst_sel:DWORD dst_unused:UNUSED_PAD src0_sel:WORD_1
	v_cvt_f32_f16_e32 v166, v187
	v_cvt_f32_f16_sdwa v167, v187 dst_sel:DWORD dst_unused:UNUSED_PAD src0_sel:WORD_1
	v_pk_mul_f32 v[164:165], v[164:165], s[84:85] op_sel_hi:[1,0]
	v_pk_mul_f32 v[166:167], v[166:167], s[84:85] op_sel_hi:[1,0]
	v_pk_fma_f32 v[72:73], v[72:73], v[136:137], v[164:165]
	v_pk_fma_f32 v[74:75], v[74:75], v[138:139], v[166:167]
	v_cvt_pk_f16_f32 v174, v72, v73
	v_cvt_pk_f16_f32 v175, v74, v75
	s_nop 1
	v_permlane16_swap_b32_e32 v172, v174
	v_permlane16_swap_b32_e32 v173, v175
	global_store_dwordx4 v177, v[172:175], s[80:81]
	s_waitcnt vmcnt(5)
	v_permlane16_swap_b32_e32 v188, v190
	v_permlane16_swap_b32_e32 v189, v191
	v_cvt_f32_f16_e32 v164, v188
	v_cvt_f32_f16_sdwa v165, v188 dst_sel:DWORD dst_unused:UNUSED_PAD src0_sel:WORD_1
	v_cvt_f32_f16_e32 v166, v189
	v_cvt_f32_f16_sdwa v167, v189 dst_sel:DWORD dst_unused:UNUSED_PAD src0_sel:WORD_1
	v_pk_mul_f32 v[164:165], v[164:165], s[84:85] op_sel_hi:[1,0]
	v_pk_mul_f32 v[166:167], v[166:167], s[84:85] op_sel_hi:[1,0]
	v_pk_fma_f32 v[76:77], v[76:77], v[140:141], v[164:165]
	v_pk_fma_f32 v[78:79], v[78:79], v[142:143], v[166:167]
	v_cvt_pk_f16_f32 v228, v76, v77
	v_cvt_pk_f16_f32 v229, v78, v79
	v_cvt_f32_f16_e32 v164, v190
	v_cvt_f32_f16_sdwa v165, v190 dst_sel:DWORD dst_unused:UNUSED_PAD src0_sel:WORD_1
	v_cvt_f32_f16_e32 v166, v191
	v_cvt_f32_f16_sdwa v167, v191 dst_sel:DWORD dst_unused:UNUSED_PAD src0_sel:WORD_1
	v_pk_mul_f32 v[164:165], v[164:165], s[84:85] op_sel_hi:[1,0]
	v_pk_mul_f32 v[166:167], v[166:167], s[84:85] op_sel_hi:[1,0]
	v_pk_fma_f32 v[80:81], v[80:81], v[144:145], v[164:165]
	v_pk_fma_f32 v[82:83], v[82:83], v[146:147], v[166:167]
	v_cvt_pk_f16_f32 v230, v80, v81
	v_cvt_pk_f16_f32 v231, v82, v83
	s_nop 1
	v_permlane16_swap_b32_e32 v228, v230
	v_permlane16_swap_b32_e32 v229, v231
	global_store_dwordx4 v177, v[228:231], s[80:81] offset:64
	v_add_u32_e32 v177, 0x8000, v177
	v_add_u32_e32 v178, 0x8000, v178
	global_load_dwordx4 v[184:187], v178, s[80:81]
	global_load_dwordx4 v[188:191], v178, s[80:81] offset:64
	s_waitcnt vmcnt(5)
	v_permlane16_swap_b32_e32 v238, v240
	v_permlane16_swap_b32_e32 v239, v241
	v_cvt_f32_f16_e32 v164, v238
	v_cvt_f32_f16_sdwa v165, v238 dst_sel:DWORD dst_unused:UNUSED_PAD src0_sel:WORD_1
	v_cvt_f32_f16_e32 v166, v239
	v_cvt_f32_f16_sdwa v167, v239 dst_sel:DWORD dst_unused:UNUSED_PAD src0_sel:WORD_1
	v_pk_mul_f32 v[164:165], v[164:165], s[84:85] op_sel_hi:[1,0]
	v_pk_mul_f32 v[166:167], v[166:167], s[84:85] op_sel_hi:[1,0]
	v_pk_fma_f32 v[84:85], v[84:85], v[132:133], v[164:165]
	v_pk_fma_f32 v[86:87], v[86:87], v[134:135], v[166:167]
	v_cvt_pk_f16_f32 v172, v84, v85
	v_cvt_pk_f16_f32 v173, v86, v87
	v_cvt_f32_f16_e32 v164, v240
	v_cvt_f32_f16_sdwa v165, v240 dst_sel:DWORD dst_unused:UNUSED_PAD src0_sel:WORD_1
	v_cvt_f32_f16_e32 v166, v241
	v_cvt_f32_f16_sdwa v167, v241 dst_sel:DWORD dst_unused:UNUSED_PAD src0_sel:WORD_1
	v_pk_mul_f32 v[164:165], v[164:165], s[84:85] op_sel_hi:[1,0]
	v_pk_mul_f32 v[166:167], v[166:167], s[84:85] op_sel_hi:[1,0]
	v_pk_fma_f32 v[88:89], v[88:89], v[136:137], v[164:165]
	v_pk_fma_f32 v[90:91], v[90:91], v[138:139], v[166:167]
	v_cvt_pk_f16_f32 v174, v88, v89
	v_cvt_pk_f16_f32 v175, v90, v91
	s_nop 1
	v_permlane16_swap_b32_e32 v172, v174
	v_permlane16_swap_b32_e32 v173, v175
	global_store_dwordx4 v177, v[172:175], s[80:81]
	s_waitcnt vmcnt(5)
	v_permlane16_swap_b32_e32 v242, v244
	v_permlane16_swap_b32_e32 v243, v245
	v_cvt_f32_f16_e32 v164, v242
	v_cvt_f32_f16_sdwa v165, v242 dst_sel:DWORD dst_unused:UNUSED_PAD src0_sel:WORD_1
	v_cvt_f32_f16_e32 v166, v243
	v_cvt_f32_f16_sdwa v167, v243 dst_sel:DWORD dst_unused:UNUSED_PAD src0_sel:WORD_1
	v_pk_mul_f32 v[164:165], v[164:165], s[84:85] op_sel_hi:[1,0]
	v_pk_mul_f32 v[166:167], v[166:167], s[84:85] op_sel_hi:[1,0]
	v_pk_fma_f32 v[92:93], v[92:93], v[140:141], v[164:165]
	v_pk_fma_f32 v[94:95], v[94:95], v[142:143], v[166:167]
	v_cvt_pk_f16_f32 v228, v92, v93
	v_cvt_pk_f16_f32 v229, v94, v95
	v_cvt_f32_f16_e32 v164, v244
	v_cvt_f32_f16_sdwa v165, v244 dst_sel:DWORD dst_unused:UNUSED_PAD src0_sel:WORD_1
	v_cvt_f32_f16_e32 v166, v245
	v_cvt_f32_f16_sdwa v167, v245 dst_sel:DWORD dst_unused:UNUSED_PAD src0_sel:WORD_1
	v_pk_mul_f32 v[164:165], v[164:165], s[84:85] op_sel_hi:[1,0]
	v_pk_mul_f32 v[166:167], v[166:167], s[84:85] op_sel_hi:[1,0]
	v_pk_fma_f32 v[96:97], v[96:97], v[144:145], v[164:165]
	v_pk_fma_f32 v[98:99], v[98:99], v[146:147], v[166:167]
	v_cvt_pk_f16_f32 v230, v96, v97
	v_cvt_pk_f16_f32 v231, v98, v99
	s_nop 1
	v_permlane16_swap_b32_e32 v228, v230
	v_permlane16_swap_b32_e32 v229, v231
	global_store_dwordx4 v177, v[228:231], s[80:81] offset:64
	v_add_u32_e32 v177, 0x8000, v177
	v_add_u32_e32 v178, 0x8000, v178
	global_load_dwordx4 v[238:241], v178, s[80:81]
	global_load_dwordx4 v[242:245], v178, s[80:81] offset:64
	s_waitcnt vmcnt(5)
	v_permlane16_swap_b32_e32 v184, v186
	v_permlane16_swap_b32_e32 v185, v187
	v_cvt_f32_f16_e32 v164, v184
	v_cvt_f32_f16_sdwa v165, v184 dst_sel:DWORD dst_unused:UNUSED_PAD src0_sel:WORD_1
	v_cvt_f32_f16_e32 v166, v185
	v_cvt_f32_f16_sdwa v167, v185 dst_sel:DWORD dst_unused:UNUSED_PAD src0_sel:WORD_1
	v_pk_mul_f32 v[164:165], v[164:165], s[84:85] op_sel_hi:[1,0]
	v_pk_mul_f32 v[166:167], v[166:167], s[84:85] op_sel_hi:[1,0]
	v_pk_fma_f32 v[100:101], v[100:101], v[132:133], v[164:165]
	v_pk_fma_f32 v[102:103], v[102:103], v[134:135], v[166:167]
	v_cvt_pk_f16_f32 v172, v100, v101
	v_cvt_pk_f16_f32 v173, v102, v103
	v_cvt_f32_f16_e32 v164, v186
	v_cvt_f32_f16_sdwa v165, v186 dst_sel:DWORD dst_unused:UNUSED_PAD src0_sel:WORD_1
	v_cvt_f32_f16_e32 v166, v187
	v_cvt_f32_f16_sdwa v167, v187 dst_sel:DWORD dst_unused:UNUSED_PAD src0_sel:WORD_1
	v_pk_mul_f32 v[164:165], v[164:165], s[84:85] op_sel_hi:[1,0]
	v_pk_mul_f32 v[166:167], v[166:167], s[84:85] op_sel_hi:[1,0]
	v_pk_fma_f32 v[104:105], v[104:105], v[136:137], v[164:165]
	v_pk_fma_f32 v[106:107], v[106:107], v[138:139], v[166:167]
	v_cvt_pk_f16_f32 v174, v104, v105
	v_cvt_pk_f16_f32 v175, v106, v107
	s_nop 1
	v_permlane16_swap_b32_e32 v172, v174
	v_permlane16_swap_b32_e32 v173, v175
	global_store_dwordx4 v177, v[172:175], s[80:81]
	s_waitcnt vmcnt(5)
	v_permlane16_swap_b32_e32 v188, v190
	v_permlane16_swap_b32_e32 v189, v191
	v_cvt_f32_f16_e32 v164, v188
	v_cvt_f32_f16_sdwa v165, v188 dst_sel:DWORD dst_unused:UNUSED_PAD src0_sel:WORD_1
	v_cvt_f32_f16_e32 v166, v189
	v_cvt_f32_f16_sdwa v167, v189 dst_sel:DWORD dst_unused:UNUSED_PAD src0_sel:WORD_1
	v_pk_mul_f32 v[164:165], v[164:165], s[84:85] op_sel_hi:[1,0]
	v_pk_mul_f32 v[166:167], v[166:167], s[84:85] op_sel_hi:[1,0]
	v_pk_fma_f32 v[108:109], v[108:109], v[140:141], v[164:165]
	v_pk_fma_f32 v[110:111], v[110:111], v[142:143], v[166:167]
	v_cvt_pk_f16_f32 v228, v108, v109
	v_cvt_pk_f16_f32 v229, v110, v111
	v_cvt_f32_f16_e32 v164, v190
	v_cvt_f32_f16_sdwa v165, v190 dst_sel:DWORD dst_unused:UNUSED_PAD src0_sel:WORD_1
	v_cvt_f32_f16_e32 v166, v191
	v_cvt_f32_f16_sdwa v167, v191 dst_sel:DWORD dst_unused:UNUSED_PAD src0_sel:WORD_1
	v_pk_mul_f32 v[164:165], v[164:165], s[84:85] op_sel_hi:[1,0]
	v_pk_mul_f32 v[166:167], v[166:167], s[84:85] op_sel_hi:[1,0]
	v_pk_fma_f32 v[112:113], v[112:113], v[144:145], v[164:165]
	v_pk_fma_f32 v[114:115], v[114:115], v[146:147], v[166:167]
	v_cvt_pk_f16_f32 v230, v112, v113
	v_cvt_pk_f16_f32 v231, v114, v115
	s_nop 1
	v_permlane16_swap_b32_e32 v228, v230
	v_permlane16_swap_b32_e32 v229, v231
	global_store_dwordx4 v177, v[228:231], s[80:81] offset:64
	v_add_u32_e32 v177, 0x8000, v177
	s_waitcnt vmcnt(3)
	v_permlane16_swap_b32_e32 v238, v240
	v_permlane16_swap_b32_e32 v239, v241
	v_cvt_f32_f16_e32 v164, v238
	v_cvt_f32_f16_sdwa v165, v238 dst_sel:DWORD dst_unused:UNUSED_PAD src0_sel:WORD_1
	v_cvt_f32_f16_e32 v166, v239
	v_cvt_f32_f16_sdwa v167, v239 dst_sel:DWORD dst_unused:UNUSED_PAD src0_sel:WORD_1
	v_pk_mul_f32 v[164:165], v[164:165], s[84:85] op_sel_hi:[1,0]
	v_pk_mul_f32 v[166:167], v[166:167], s[84:85] op_sel_hi:[1,0]
	v_pk_fma_f32 v[116:117], v[116:117], v[132:133], v[164:165]
	v_pk_fma_f32 v[118:119], v[118:119], v[134:135], v[166:167]
	v_cvt_pk_f16_f32 v172, v116, v117
	v_cvt_pk_f16_f32 v173, v118, v119
	v_cvt_f32_f16_e32 v164, v240
	v_cvt_f32_f16_sdwa v165, v240 dst_sel:DWORD dst_unused:UNUSED_PAD src0_sel:WORD_1
	v_cvt_f32_f16_e32 v166, v241
	v_cvt_f32_f16_sdwa v167, v241 dst_sel:DWORD dst_unused:UNUSED_PAD src0_sel:WORD_1
	v_pk_mul_f32 v[164:165], v[164:165], s[84:85] op_sel_hi:[1,0]
	v_pk_mul_f32 v[166:167], v[166:167], s[84:85] op_sel_hi:[1,0]
	v_pk_fma_f32 v[120:121], v[120:121], v[136:137], v[164:165]
	v_pk_fma_f32 v[122:123], v[122:123], v[138:139], v[166:167]
	v_cvt_pk_f16_f32 v174, v120, v121
	v_cvt_pk_f16_f32 v175, v122, v123
	s_nop 1
	v_permlane16_swap_b32_e32 v172, v174
	v_permlane16_swap_b32_e32 v173, v175
	global_store_dwordx4 v177, v[172:175], s[80:81]
	s_waitcnt vmcnt(3)
	v_permlane16_swap_b32_e32 v242, v244
	v_permlane16_swap_b32_e32 v243, v245
	v_cvt_f32_f16_e32 v164, v242
	v_cvt_f32_f16_sdwa v165, v242 dst_sel:DWORD dst_unused:UNUSED_PAD src0_sel:WORD_1
	v_cvt_f32_f16_e32 v166, v243
	v_cvt_f32_f16_sdwa v167, v243 dst_sel:DWORD dst_unused:UNUSED_PAD src0_sel:WORD_1
	v_pk_mul_f32 v[164:165], v[164:165], s[84:85] op_sel_hi:[1,0]
	v_pk_mul_f32 v[166:167], v[166:167], s[84:85] op_sel_hi:[1,0]
	v_pk_fma_f32 v[124:125], v[124:125], v[140:141], v[164:165]
	v_pk_fma_f32 v[126:127], v[126:127], v[142:143], v[166:167]
	v_cvt_pk_f16_f32 v228, v124, v125
	v_cvt_pk_f16_f32 v229, v126, v127
	v_cvt_f32_f16_e32 v164, v244
	v_cvt_f32_f16_sdwa v165, v244 dst_sel:DWORD dst_unused:UNUSED_PAD src0_sel:WORD_1
	v_cvt_f32_f16_e32 v166, v245
	v_cvt_f32_f16_sdwa v167, v245 dst_sel:DWORD dst_unused:UNUSED_PAD src0_sel:WORD_1
	v_pk_mul_f32 v[164:165], v[164:165], s[84:85] op_sel_hi:[1,0]
	v_pk_mul_f32 v[166:167], v[166:167], s[84:85] op_sel_hi:[1,0]
	v_pk_fma_f32 v[128:129], v[128:129], v[144:145], v[164:165]
	v_pk_fma_f32 v[130:131], v[130:131], v[146:147], v[166:167]
	v_cvt_pk_f16_f32 v230, v128, v129
	v_cvt_pk_f16_f32 v231, v130, v131
	s_nop 1
	v_permlane16_swap_b32_e32 v228, v230
	v_permlane16_swap_b32_e32 v229, v231
	global_store_dwordx4 v177, v[228:231], s[80:81] offset:64
	s_nop 1
	s_branch .LBB0_88

.LBB0_760:
	s_andn2_b64 vcc, exec, s[28:29]
	s_cbranch_vccnz .LBB0_853
	v_readlane_b32 s24, v236, 3
	v_readlane_b32 s25, v236, 4
	s_andn2_b64 vcc, exec, s[24:25]
	s_cbranch_vccnz .LBB0_814
	s_add_u32 s26, s44, 0xaa08000
	s_addc_u32 s27, s45, 0
	v_readlane_b32 s24, v236, 5
	v_readlane_b32 s25, v236, 9
	s_lshr_b32 s28, s25, 2
	s_lshl_b32 s28, s28, 3
	s_and_b32 s25, s25, 3
	s_lshl_b32 s25, s25, 1
	s_or_b32 s25, s25, s28
	s_branch .LBB0_764

.LBB0_768:
	s_waitcnt lgkmcnt(0)
	s_lshl_b64 s[36:37], s[90:91], 13
	s_add_u32 s36, s36, s28
	s_addc_u32 s37, s37, s29
	s_and_b32 s30, s25, 7
	s_lshl_b32 s30, s30, 7
	s_lshl_b32 s53, s30, 13
	s_add_u32 s50, s48, s53
	s_addc_u32 s51, s49, 0
	v_readfirstlane_b32 s53, v200
	s_lshr_b32 s53, s53, 6
	s_lshl_b32 s31, s53, 11
	s_add_u32 s31, s31, 16
	s_lshl_b32 s53, s53, 18
	s_add_u32 s36, s36, s53
	s_addc_u32 s37, s37, 0
	s_add_u32 s50, s50, s53
	s_addc_u32 s51, s51, 0
	v_bfe_u32 v173, v200, 4, 2
	v_sub_u32_e32 v173, 0, v173
	v_and_b32_e32 v173, 3, v173
	v_and_b32_e32 v172, 3, v200
	v_xor_b32_e32 v172, v172, v173
	v_bfe_u32 v173, v200, 2, 4
	v_lshlrev_b32_e32 v173, 13, v173
	v_lshl_or_b32 v170, v172, 4, v173
	v_add_u32_e32 v171, 0x20000, v170
	v_bfe_u32 v172, v200, 2, 2
	v_sub_u32_e32 v172, 0, v172
	v_and_b32_e32 v172, 3, v172
	v_bfe_u32 v173, v200, 4, 2
	v_xor_b32_e32 v172, v172, v173
	v_and_b32_e32 v173, 15, v200
	v_bfe_u32 v174, v200, 8, 1
	v_lshl_or_b32 v174, v174, 7, v173
	v_lshlrev_b32_e32 v174, 6, v174
	v_lshl_or_b32 v164, v172, 4, v174
	v_bfe_u32 v174, v200, 6, 2
	v_lshl_or_b32 v174, v174, 6, v173
	v_lshlrev_b32_e32 v174, 6, v174
	v_lshl_or_b32 v165, v172, 4, v174
	v_add_u32_e32 v165, 0x4000, v165
	v_bfe_u32 v172, v200, 6, 2
	v_bfe_u32 v173, v200, 4, 2
	v_lshlrev_b32_e32 v172, 6, v172
	v_lshl_or_b32 v172, v173, 2, v172
	v_add_u32_e32 v172, s30, v172
	v_lshlrev_b32_e32 v172, 2, v172
	global_load_dwordx4 v[132:135], v172, s[42:43]
	global_load_dwordx4 v[136:139], v172, s[42:43] offset:64
	global_load_dwordx4 v[140:143], v172, s[42:43] offset:128
	global_load_dwordx4 v[144:147], v172, s[42:43] offset:192
	s_mov_b32 s34, s31
	s_mov_b32 m0, s34
	s_nop 0
	global_load_lds_dwordx4 v170, s[36:37]
	s_add_u32 m0, s34, 0x400
	s_nop 0
	global_load_lds_dwordx4 v171, s[36:37]
	s_add_u32 m0, s34, 0x4000
	s_nop 0
	global_load_lds_dwordx4 v170, s[50:51]
	s_add_u32 m0, s34, 0x4400
	s_nop 0
	global_load_lds_dwordx4 v171, s[50:51]
	s_add_u32 s36, s36, 64
	s_addc_u32 s37, s37, 0
	s_add_u32 s50, s50, 64
	s_addc_u32 s51, s51, 0
	s_add_u32 s34, s31, 0x8000
	s_mov_b32 m0, s34
	s_nop 0
	global_load_lds_dwordx4 v170, s[36:37]
	s_add_u32 m0, s34, 0x400
	s_nop 0
	global_load_lds_dwordx4 v171, s[36:37]
	s_add_u32 m0, s34, 0x4000
	s_nop 0
	global_load_lds_dwordx4 v170, s[50:51]
	s_add_u32 m0, s34, 0x4400
	s_nop 0
	global_load_lds_dwordx4 v171, s[50:51]
	s_add_u32 s36, s36, 64
	s_addc_u32 s37, s37, 0
	s_add_u32 s50, s50, 64
	s_addc_u32 s51, s51, 0
	s_add_u32 s34, s31, 0x10000
	s_mov_b32 m0, s34
	s_nop 0
	global_load_lds_dwordx4 v170, s[36:37]
	s_add_u32 m0, s34, 0x400
	s_nop 0
	global_load_lds_dwordx4 v171, s[36:37]
	s_add_u32 m0, s34, 0x4000
	s_nop 0
	global_load_lds_dwordx4 v170, s[50:51]
	s_add_u32 m0, s34, 0x4400
	s_nop 0
	global_load_lds_dwordx4 v171, s[50:51]
	s_add_u32 s36, s36, 64
	s_addc_u32 s37, s37, 0
	s_add_u32 s50, s50, 64
	s_addc_u32 s51, s51, 0
	s_add_u32 s34, s31, 0x18000
	s_mov_b32 m0, s34
	s_nop 0
	global_load_lds_dwordx4 v170, s[36:37]
	s_add_u32 m0, s34, 0x400
	s_nop 0
	global_load_lds_dwordx4 v171, s[36:37]
	s_add_u32 m0, s34, 0x4000
	s_nop 0
	global_load_lds_dwordx4 v170, s[50:51]
	s_add_u32 m0, s34, 0x4400
	s_nop 0
	global_load_lds_dwordx4 v171, s[50:51]
	s_add_u32 s36, s36, 64
	s_addc_u32 s37, s37, 0
	s_add_u32 s50, s50, 64
	s_addc_u32 s51, s51, 0
	s_waitcnt vmcnt(16)
	v_mov_b32_e32 v4, v132
	v_mov_b32_e32 v5, v133
	v_mov_b32_e32 v6, v134
	v_mov_b32_e32 v7, v135
	v_mov_b32_e32 v8, v136
	v_mov_b32_e32 v9, v137
	v_mov_b32_e32 v10, v138
	v_mov_b32_e32 v11, v139
	v_mov_b32_e32 v12, v140
	v_mov_b32_e32 v13, v141
	v_mov_b32_e32 v14, v142
	v_mov_b32_e32 v15, v143
	v_mov_b32_e32 v16, v144
	v_mov_b32_e32 v17, v145
	v_mov_b32_e32 v18, v146
	v_mov_b32_e32 v19, v147
	v_mov_b32_e32 v20, v132
	v_mov_b32_e32 v21, v133
	v_mov_b32_e32 v22, v134
	v_mov_b32_e32 v23, v135
	v_mov_b32_e32 v24, v136
	v_mov_b32_e32 v25, v137
	v_mov_b32_e32 v26, v138
	v_mov_b32_e32 v27, v139
	v_mov_b32_e32 v28, v140
	v_mov_b32_e32 v29, v141
	v_mov_b32_e32 v30, v142
	v_mov_b32_e32 v31, v143
	v_mov_b32_e32 v32, v144
	v_mov_b32_e32 v33, v145
	v_mov_b32_e32 v34, v146
	v_mov_b32_e32 v35, v147
	v_mov_b32_e32 v36, v132
	v_mov_b32_e32 v37, v133
	v_mov_b32_e32 v38, v134
	v_mov_b32_e32 v39, v135
	v_mov_b32_e32 v40, v136
	v_mov_b32_e32 v41, v137
	v_mov_b32_e32 v42, v138
	v_mov_b32_e32 v43, v139
	v_mov_b32_e32 v44, v140
	v_mov_b32_e32 v45, v141
	v_mov_b32_e32 v46, v142
	v_mov_b32_e32 v47, v143
	v_mov_b32_e32 v48, v144
	v_mov_b32_e32 v49, v145
	v_mov_b32_e32 v50, v146
	v_mov_b32_e32 v51, v147
	v_mov_b32_e32 v52, v132
	v_mov_b32_e32 v53, v133
	v_mov_b32_e32 v54, v134
	v_mov_b32_e32 v55, v135
	v_mov_b32_e32 v56, v136
	v_mov_b32_e32 v57, v137
	v_mov_b32_e32 v58, v138
	v_mov_b32_e32 v59, v139
	v_mov_b32_e32 v60, v140
	v_mov_b32_e32 v61, v141
	v_mov_b32_e32 v62, v142
	v_mov_b32_e32 v63, v143
	v_mov_b32_e32 v64, v144
	v_mov_b32_e32 v65, v145
	v_mov_b32_e32 v66, v146
	v_mov_b32_e32 v67, v147
	v_mov_b32_e32 v68, v132
	v_mov_b32_e32 v69, v133
	v_mov_b32_e32 v70, v134
	v_mov_b32_e32 v71, v135
	v_mov_b32_e32 v72, v136
	v_mov_b32_e32 v73, v137
	v_mov_b32_e32 v74, v138
	v_mov_b32_e32 v75, v139
	v_mov_b32_e32 v76, v140
	v_mov_b32_e32 v77, v141
	v_mov_b32_e32 v78, v142
	v_mov_b32_e32 v79, v143
	v_mov_b32_e32 v80, v144
	v_mov_b32_e32 v81, v145
	v_mov_b32_e32 v82, v146
	v_mov_b32_e32 v83, v147
	v_mov_b32_e32 v84, v132
	v_mov_b32_e32 v85, v133
	v_mov_b32_e32 v86, v134
	v_mov_b32_e32 v87, v135
	v_mov_b32_e32 v88, v136
	v_mov_b32_e32 v89, v137
	v_mov_b32_e32 v90, v138
	v_mov_b32_e32 v91, v139
	v_mov_b32_e32 v92, v140
	v_mov_b32_e32 v93, v141
	v_mov_b32_e32 v94, v142
	v_mov_b32_e32 v95, v143
	v_mov_b32_e32 v96, v144
	v_mov_b32_e32 v97, v145
	v_mov_b32_e32 v98, v146
	v_mov_b32_e32 v99, v147
	v_mov_b32_e32 v100, v132
	v_mov_b32_e32 v101, v133
	v_mov_b32_e32 v102, v134
	v_mov_b32_e32 v103, v135
	v_mov_b32_e32 v104, v136
	v_mov_b32_e32 v105, v137
	v_mov_b32_e32 v106, v138
	v_mov_b32_e32 v107, v139
	v_mov_b32_e32 v108, v140
	v_mov_b32_e32 v109, v141
	v_mov_b32_e32 v110, v142
	v_mov_b32_e32 v111, v143
	v_mov_b32_e32 v112, v144
	v_mov_b32_e32 v113, v145
	v_mov_b32_e32 v114, v146
	v_mov_b32_e32 v115, v147
	v_mov_b32_e32 v116, v132
	v_mov_b32_e32 v117, v133
	v_mov_b32_e32 v118, v134
	v_mov_b32_e32 v119, v135
	v_mov_b32_e32 v120, v136
	v_mov_b32_e32 v121, v137
	v_mov_b32_e32 v122, v138
	v_mov_b32_e32 v123, v139
	v_mov_b32_e32 v124, v140
	v_mov_b32_e32 v125, v141
	v_mov_b32_e32 v126, v142
	v_mov_b32_e32 v127, v143
	v_mov_b32_e32 v128, v144
	v_mov_b32_e32 v129, v145
	v_mov_b32_e32 v130, v146
	v_mov_b32_e32 v131, v147
	s_waitcnt vmcnt(12)
	s_barrier
	s_mov_b32 s32, 0
	s_mov_b32 s52, 0
	s_nop 1
	v_add_u32_e32 v168, s32, v165
	v_add_u32_e32 v169, s32, v164
	ds_read_b128 v[132:135], v168 offset:16
	ds_read_b128 v[136:139], v168 offset:1040
	ds_read_b128 v[140:143], v168 offset:2064
	ds_read_b128 v[144:147], v168 offset:3088
	ds_read_b128 v[184:187], v169 offset:16
	ds_read_b128 v[188:191], v169 offset:1040
	ds_read_b128 v[192:195], v169 offset:2064
	ds_read_b128 v[196:199], v169 offset:3088
	s_waitcnt lgkmcnt(0)
.Lt_mlp2a:
	v_add_u32_e32 v169, s32, v164
	v_mfma_f32_16x16x32_f16 v[4:7], v[132:135], v[184:187], v[4:7]
	ds_read_b128 v[238:241], v169 offset:4112
	v_mfma_f32_16x16x32_f16 v[8:11], v[136:139], v[184:187], v[8:11]
	ds_read_b128 v[242:245], v169 offset:5136
	v_mfma_f32_16x16x32_f16 v[12:15], v[140:143], v[184:187], v[12:15]
	ds_read_b128 v[246:249], v169 offset:6160
	v_mfma_f32_16x16x32_f16 v[16:19], v[144:147], v[184:187], v[16:19]
	ds_read_b128 v[250:253], v169 offset:7184
	v_mfma_f32_16x16x32_f16 v[20:23], v[132:135], v[188:191], v[20:23]
	v_mfma_f32_16x16x32_f16 v[24:27], v[136:139], v[188:191], v[24:27]
	v_mfma_f32_16x16x32_f16 v[28:31], v[140:143], v[188:191], v[28:31]
	v_mfma_f32_16x16x32_f16 v[32:35], v[144:147], v[188:191], v[32:35]
	v_mfma_f32_16x16x32_f16 v[36:39], v[132:135], v[192:195], v[36:39]
	v_mfma_f32_16x16x32_f16 v[40:43], v[136:139], v[192:195], v[40:43]
	v_mfma_f32_16x16x32_f16 v[44:47], v[140:143], v[192:195], v[44:47]
	v_mfma_f32_16x16x32_f16 v[48:51], v[144:147], v[192:195], v[48:51]
	v_mfma_f32_16x16x32_f16 v[52:55], v[132:135], v[196:199], v[52:55]
	v_mfma_f32_16x16x32_f16 v[56:59], v[136:139], v[196:199], v[56:59]
	v_mfma_f32_16x16x32_f16 v[60:63], v[140:143], v[196:199], v[60:63]
	v_mfma_f32_16x16x32_f16 v[64:67], v[144:147], v[196:199], v[64:67]
	s_waitcnt vmcnt(8) lgkmcnt(0)
	s_barrier
	s_add_i32 s34, s32, 0x8000
	s_cmp_lg_u32 s32, 0x18000
	s_cselect_b32 s34, s34, 0
	v_add_u32_e32 v168, s34, v165
	v_add_u32_e32 v169, s34, v164
	s_add_u32 vcc_lo, s31, s32
	v_mfma_f32_16x16x32_f16 v[68:71], v[132:135], v[238:241], v[68:71]
	ds_read_b128 v[148:151], v168 offset:16
	ds_read_b128 v[184:187], v169 offset:16
	v_mfma_f32_16x16x32_f16 v[72:75], v[136:139], v[238:241], v[72:75]
	ds_read_b128 v[152:155], v168 offset:1040
	ds_read_b128 v[188:191], v169 offset:1040
	v_mfma_f32_16x16x32_f16 v[76:79], v[140:143], v[238:241], v[76:79]
	ds_read_b128 v[156:159], v168 offset:2064
	ds_read_b128 v[192:195], v169 offset:2064
	v_mfma_f32_16x16x32_f16 v[80:83], v[144:147], v[238:241], v[80:83]
	ds_read_b128 v[160:163], v168 offset:3088
	ds_read_b128 v[196:199], v169 offset:3088
	v_mfma_f32_16x16x32_f16 v[84:87], v[132:135], v[242:245], v[84:87]
	v_mfma_f32_16x16x32_f16 v[88:91], v[136:139], v[242:245], v[88:91]
	v_mfma_f32_16x16x32_f16 v[92:95], v[140:143], v[242:245], v[92:95]
	v_mfma_f32_16x16x32_f16 v[96:99], v[144:147], v[242:245], v[96:99]
	v_mfma_f32_16x16x32_f16 v[100:103], v[132:135], v[246:249], v[100:103]
	s_mov_b32 m0, vcc_lo
	s_nop 0
	global_load_lds_dwordx4 v170, s[36:37]
	v_mfma_f32_16x16x32_f16 v[104:107], v[136:139], v[246:249], v[104:107]
	s_add_u32 m0, vcc_lo, 0x400
	s_nop 0
	global_load_lds_dwordx4 v171, s[36:37]
	v_mfma_f32_16x16x32_f16 v[108:111], v[140:143], v[246:249], v[108:111]
	s_add_u32 m0, vcc_lo, 0x4000
	s_nop 0
	global_load_lds_dwordx4 v170, s[50:51]
	v_mfma_f32_16x16x32_f16 v[112:115], v[144:147], v[246:249], v[112:115]
	s_add_u32 m0, vcc_lo, 0x4400
	s_nop 0
	global_load_lds_dwordx4 v171, s[50:51]
	v_mfma_f32_16x16x32_f16 v[116:119], v[132:135], v[250:253], v[116:119]
	v_mfma_f32_16x16x32_f16 v[120:123], v[136:139], v[250:253], v[120:123]
	v_mfma_f32_16x16x32_f16 v[124:127], v[140:143], v[250:253], v[124:127]
	v_mfma_f32_16x16x32_f16 v[128:131], v[144:147], v[250:253], v[128:131]
	s_waitcnt lgkmcnt(0)
	s_mov_b32 s32, s34
	s_add_u32 s36, s36, 64
	s_addc_u32 s37, s37, 0
	s_add_u32 s50, s50, 64
	s_addc_u32 s51, s51, 0
	v_add_u32_e32 v169, s32, v164
	v_mfma_f32_16x16x32_f16 v[4:7], v[148:151], v[184:187], v[4:7]
	ds_read_b128 v[238:241], v169 offset:4112
	v_mfma_f32_16x16x32_f16 v[8:11], v[152:155], v[184:187], v[8:11]
	ds_read_b128 v[242:245], v169 offset:5136
	v_mfma_f32_16x16x32_f16 v[12:15], v[156:159], v[184:187], v[12:15]
	ds_read_b128 v[246:249], v169 offset:6160
	v_mfma_f32_16x16x32_f16 v[16:19], v[160:163], v[184:187], v[16:19]
	ds_read_b128 v[250:253], v169 offset:7184
	v_mfma_f32_16x16x32_f16 v[20:23], v[148:151], v[188:191], v[20:23]
	v_mfma_f32_16x16x32_f16 v[24:27], v[152:155], v[188:191], v[24:27]
	v_mfma_f32_16x16x32_f16 v[28:31], v[156:159], v[188:191], v[28:31]
	v_mfma_f32_16x16x32_f16 v[32:35], v[160:163], v[188:191], v[32:35]
	v_mfma_f32_16x16x32_f16 v[36:39], v[148:151], v[192:195], v[36:39]
	v_mfma_f32_16x16x32_f16 v[40:43], v[152:155], v[192:195], v[40:43]
	v_mfma_f32_16x16x32_f16 v[44:47], v[156:159], v[192:195], v[44:47]
	v_mfma_f32_16x16x32_f16 v[48:51], v[160:163], v[192:195], v[48:51]
	v_mfma_f32_16x16x32_f16 v[52:55], v[148:151], v[196:199], v[52:55]
	v_mfma_f32_16x16x32_f16 v[56:59], v[152:155], v[196:199], v[56:59]
	v_mfma_f32_16x16x32_f16 v[60:63], v[156:159], v[196:199], v[60:63]
	v_mfma_f32_16x16x32_f16 v[64:67], v[160:163], v[196:199], v[64:67]
	s_waitcnt vmcnt(8) lgkmcnt(0)
	s_barrier
	s_add_i32 s34, s32, 0x8000
	s_cmp_lg_u32 s32, 0x18000
	s_cselect_b32 s34, s34, 0
	v_add_u32_e32 v168, s34, v165
	v_add_u32_e32 v169, s34, v164
	s_add_u32 vcc_lo, s31, s32
	v_mfma_f32_16x16x32_f16 v[68:71], v[148:151], v[238:241], v[68:71]
	ds_read_b128 v[132:135], v168 offset:16
	ds_read_b128 v[184:187], v169 offset:16
	v_mfma_f32_16x16x32_f16 v[72:75], v[152:155], v[238:241], v[72:75]
	ds_read_b128 v[136:139], v168 offset:1040
	ds_read_b128 v[188:191], v169 offset:1040
	v_mfma_f32_16x16x32_f16 v[76:79], v[156:159], v[238:241], v[76:79]
	ds_read_b128 v[140:143], v168 offset:2064
	ds_read_b128 v[192:195], v169 offset:2064
	v_mfma_f32_16x16x32_f16 v[80:83], v[160:163], v[238:241], v[80:83]
	ds_read_b128 v[144:147], v168 offset:3088
	ds_read_b128 v[196:199], v169 offset:3088
	v_mfma_f32_16x16x32_f16 v[84:87], v[148:151], v[242:245], v[84:87]
	v_mfma_f32_16x16x32_f16 v[88:91], v[152:155], v[242:245], v[88:91]
	v_mfma_f32_16x16x32_f16 v[92:95], v[156:159], v[242:245], v[92:95]
	v_mfma_f32_16x16x32_f16 v[96:99], v[160:163], v[242:245], v[96:99]
	v_mfma_f32_16x16x32_f16 v[100:103], v[148:151], v[246:249], v[100:103]
	s_mov_b32 m0, vcc_lo
	s_nop 0
	global_load_lds_dwordx4 v170, s[36:37]
	v_mfma_f32_16x16x32_f16 v[104:107], v[152:155], v[246:249], v[104:107]
	s_add_u32 m0, vcc_lo, 0x400
	s_nop 0
	global_load_lds_dwordx4 v171, s[36:37]
	v_mfma_f32_16x16x32_f16 v[108:111], v[156:159], v[246:249], v[108:111]
	s_add_u32 m0, vcc_lo, 0x4000
	s_nop 0
	global_load_lds_dwordx4 v170, s[50:51]
	v_mfma_f32_16x16x32_f16 v[112:115], v[160:163], v[246:249], v[112:115]
	s_add_u32 m0, vcc_lo, 0x4400
	s_nop 0
	global_load_lds_dwordx4 v171, s[50:51]
	v_mfma_f32_16x16x32_f16 v[116:119], v[148:151], v[250:253], v[116:119]
	v_mfma_f32_16x16x32_f16 v[120:123], v[152:155], v[250:253], v[120:123]
	v_mfma_f32_16x16x32_f16 v[124:127], v[156:159], v[250:253], v[124:127]
	v_mfma_f32_16x16x32_f16 v[128:131], v[160:163], v[250:253], v[128:131]
	s_waitcnt lgkmcnt(0)
	s_mov_b32 s32, s34
	s_add_u32 s36, s36, 64
	s_addc_u32 s37, s37, 0
	s_add_u32 s50, s50, 64
	s_addc_u32 s51, s51, 0
	s_add_i32 s52, s52, 2
	s_cmp_lt_u32 s52, 124
	s_cbranch_scc1 .Lt_mlp2a
	v_add_u32_e32 v169, s32, v164
	v_mfma_f32_16x16x32_f16 v[4:7], v[132:135], v[184:187], v[4:7]
	ds_read_b128 v[238:241], v169 offset:4112
	v_mfma_f32_16x16x32_f16 v[8:11], v[136:139], v[184:187], v[8:11]
	ds_read_b128 v[242:245], v169 offset:5136
	v_mfma_f32_16x16x32_f16 v[12:15], v[140:143], v[184:187], v[12:15]
	ds_read_b128 v[246:249], v169 offset:6160
	v_mfma_f32_16x16x32_f16 v[16:19], v[144:147], v[184:187], v[16:19]
	ds_read_b128 v[250:253], v169 offset:7184
	v_mfma_f32_16x16x32_f16 v[20:23], v[132:135], v[188:191], v[20:23]
	v_mfma_f32_16x16x32_f16 v[24:27], v[136:139], v[188:191], v[24:27]
	v_mfma_f32_16x16x32_f16 v[28:31], v[140:143], v[188:191], v[28:31]
	v_mfma_f32_16x16x32_f16 v[32:35], v[144:147], v[188:191], v[32:35]
	v_mfma_f32_16x16x32_f16 v[36:39], v[132:135], v[192:195], v[36:39]
	v_mfma_f32_16x16x32_f16 v[40:43], v[136:139], v[192:195], v[40:43]
	v_mfma_f32_16x16x32_f16 v[44:47], v[140:143], v[192:195], v[44:47]
	v_mfma_f32_16x16x32_f16 v[48:51], v[144:147], v[192:195], v[48:51]
	v_mfma_f32_16x16x32_f16 v[52:55], v[132:135], v[196:199], v[52:55]
	v_mfma_f32_16x16x32_f16 v[56:59], v[136:139], v[196:199], v[56:59]
	v_mfma_f32_16x16x32_f16 v[60:63], v[140:143], v[196:199], v[60:63]
	v_mfma_f32_16x16x32_f16 v[64:67], v[144:147], v[196:199], v[64:67]
	s_waitcnt vmcnt(8) lgkmcnt(0)
	s_barrier
	s_add_i32 s34, s32, 0x8000
	s_cmp_lg_u32 s32, 0x18000
	s_cselect_b32 s34, s34, 0
	v_add_u32_e32 v168, s34, v165
	v_add_u32_e32 v169, s34, v164
	v_mfma_f32_16x16x32_f16 v[68:71], v[132:135], v[238:241], v[68:71]
	ds_read_b128 v[148:151], v168 offset:16
	ds_read_b128 v[184:187], v169 offset:16
	v_mfma_f32_16x16x32_f16 v[72:75], v[136:139], v[238:241], v[72:75]
	ds_read_b128 v[152:155], v168 offset:1040
	ds_read_b128 v[188:191], v169 offset:1040
	v_mfma_f32_16x16x32_f16 v[76:79], v[140:143], v[238:241], v[76:79]
	ds_read_b128 v[156:159], v168 offset:2064
	ds_read_b128 v[192:195], v169 offset:2064
	v_mfma_f32_16x16x32_f16 v[80:83], v[144:147], v[238:241], v[80:83]
	ds_read_b128 v[160:163], v168 offset:3088
	ds_read_b128 v[196:199], v169 offset:3088
	v_mfma_f32_16x16x32_f16 v[84:87], v[132:135], v[242:245], v[84:87]
	v_mfma_f32_16x16x32_f16 v[88:91], v[136:139], v[242:245], v[88:91]
	v_mfma_f32_16x16x32_f16 v[92:95], v[140:143], v[242:245], v[92:95]
	v_mfma_f32_16x16x32_f16 v[96:99], v[144:147], v[242:245], v[96:99]
	v_mfma_f32_16x16x32_f16 v[100:103], v[132:135], v[246:249], v[100:103]
	v_mfma_f32_16x16x32_f16 v[104:107], v[136:139], v[246:249], v[104:107]
	v_mfma_f32_16x16x32_f16 v[108:111], v[140:143], v[246:249], v[108:111]
	v_mfma_f32_16x16x32_f16 v[112:115], v[144:147], v[246:249], v[112:115]
	v_mfma_f32_16x16x32_f16 v[116:119], v[132:135], v[250:253], v[116:119]
	v_mfma_f32_16x16x32_f16 v[120:123], v[136:139], v[250:253], v[120:123]
	v_mfma_f32_16x16x32_f16 v[124:127], v[140:143], v[250:253], v[124:127]
	v_mfma_f32_16x16x32_f16 v[128:131], v[144:147], v[250:253], v[128:131]
	s_waitcnt lgkmcnt(0)
	s_mov_b32 s32, s34
	v_add_u32_e32 v169, s32, v164
	v_mfma_f32_16x16x32_f16 v[4:7], v[148:151], v[184:187], v[4:7]
	ds_read_b128 v[238:241], v169 offset:4112
	v_mfma_f32_16x16x32_f16 v[8:11], v[152:155], v[184:187], v[8:11]
	ds_read_b128 v[242:245], v169 offset:5136
	v_mfma_f32_16x16x32_f16 v[12:15], v[156:159], v[184:187], v[12:15]
	ds_read_b128 v[246:249], v169 offset:6160
	v_mfma_f32_16x16x32_f16 v[16:19], v[160:163], v[184:187], v[16:19]
	ds_read_b128 v[250:253], v169 offset:7184
	v_mfma_f32_16x16x32_f16 v[20:23], v[148:151], v[188:191], v[20:23]
	v_mfma_f32_16x16x32_f16 v[24:27], v[152:155], v[188:191], v[24:27]
	v_mfma_f32_16x16x32_f16 v[28:31], v[156:159], v[188:191], v[28:31]
	v_mfma_f32_16x16x32_f16 v[32:35], v[160:163], v[188:191], v[32:35]
	v_mfma_f32_16x16x32_f16 v[36:39], v[148:151], v[192:195], v[36:39]
	v_mfma_f32_16x16x32_f16 v[40:43], v[152:155], v[192:195], v[40:43]
	v_mfma_f32_16x16x32_f16 v[44:47], v[156:159], v[192:195], v[44:47]
	v_mfma_f32_16x16x32_f16 v[48:51], v[160:163], v[192:195], v[48:51]
	v_mfma_f32_16x16x32_f16 v[52:55], v[148:151], v[196:199], v[52:55]
	v_mfma_f32_16x16x32_f16 v[56:59], v[152:155], v[196:199], v[56:59]
	v_mfma_f32_16x16x32_f16 v[60:63], v[156:159], v[196:199], v[60:63]
	v_mfma_f32_16x16x32_f16 v[64:67], v[160:163], v[196:199], v[64:67]
	s_waitcnt vmcnt(4) lgkmcnt(0)
	s_barrier
	s_add_i32 s34, s32, 0x8000
	s_cmp_lg_u32 s32, 0x18000
	s_cselect_b32 s34, s34, 0
	v_add_u32_e32 v168, s34, v165
	v_add_u32_e32 v169, s34, v164
	v_mfma_f32_16x16x32_f16 v[68:71], v[148:151], v[238:241], v[68:71]
	ds_read_b128 v[132:135], v168 offset:16
	ds_read_b128 v[184:187], v169 offset:16
	v_mfma_f32_16x16x32_f16 v[72:75], v[152:155], v[238:241], v[72:75]
	ds_read_b128 v[136:139], v168 offset:1040
	ds_read_b128 v[188:191], v169 offset:1040
	v_mfma_f32_16x16x32_f16 v[76:79], v[156:159], v[238:241], v[76:79]
	ds_read_b128 v[140:143], v168 offset:2064
	ds_read_b128 v[192:195], v169 offset:2064
	v_mfma_f32_16x16x32_f16 v[80:83], v[160:163], v[238:241], v[80:83]
	ds_read_b128 v[144:147], v168 offset:3088
	ds_read_b128 v[196:199], v169 offset:3088
	v_mfma_f32_16x16x32_f16 v[84:87], v[148:151], v[242:245], v[84:87]
	v_mfma_f32_16x16x32_f16 v[88:91], v[152:155], v[242:245], v[88:91]
	v_mfma_f32_16x16x32_f16 v[92:95], v[156:159], v[242:245], v[92:95]
	v_mfma_f32_16x16x32_f16 v[96:99], v[160:163], v[242:245], v[96:99]
	v_mfma_f32_16x16x32_f16 v[100:103], v[148:151], v[246:249], v[100:103]
	v_mfma_f32_16x16x32_f16 v[104:107], v[152:155], v[246:249], v[104:107]
	v_mfma_f32_16x16x32_f16 v[108:111], v[156:159], v[246:249], v[108:111]
	v_mfma_f32_16x16x32_f16 v[112:115], v[160:163], v[246:249], v[112:115]
	v_mfma_f32_16x16x32_f16 v[116:119], v[148:151], v[250:253], v[116:119]
	v_mfma_f32_16x16x32_f16 v[120:123], v[152:155], v[250:253], v[120:123]
	v_mfma_f32_16x16x32_f16 v[124:127], v[156:159], v[250:253], v[124:127]
	v_mfma_f32_16x16x32_f16 v[128:131], v[160:163], v[250:253], v[128:131]
	s_waitcnt lgkmcnt(0)
	s_mov_b32 s32, s34
	v_add_u32_e32 v169, s32, v164
	v_mfma_f32_16x16x32_f16 v[4:7], v[132:135], v[184:187], v[4:7]
	ds_read_b128 v[238:241], v169 offset:4112
	v_mfma_f32_16x16x32_f16 v[8:11], v[136:139], v[184:187], v[8:11]
	ds_read_b128 v[242:245], v169 offset:5136
	v_mfma_f32_16x16x32_f16 v[12:15], v[140:143], v[184:187], v[12:15]
	ds_read_b128 v[246:249], v169 offset:6160
	v_mfma_f32_16x16x32_f16 v[16:19], v[144:147], v[184:187], v[16:19]
	ds_read_b128 v[250:253], v169 offset:7184
	v_mfma_f32_16x16x32_f16 v[20:23], v[132:135], v[188:191], v[20:23]
	v_mfma_f32_16x16x32_f16 v[24:27], v[136:139], v[188:191], v[24:27]
	v_mfma_f32_16x16x32_f16 v[28:31], v[140:143], v[188:191], v[28:31]
	v_mfma_f32_16x16x32_f16 v[32:35], v[144:147], v[188:191], v[32:35]
	v_mfma_f32_16x16x32_f16 v[36:39], v[132:135], v[192:195], v[36:39]
	v_mfma_f32_16x16x32_f16 v[40:43], v[136:139], v[192:195], v[40:43]
	v_mfma_f32_16x16x32_f16 v[44:47], v[140:143], v[192:195], v[44:47]
	v_mfma_f32_16x16x32_f16 v[48:51], v[144:147], v[192:195], v[48:51]
	v_mfma_f32_16x16x32_f16 v[52:55], v[132:135], v[196:199], v[52:55]
	v_mfma_f32_16x16x32_f16 v[56:59], v[136:139], v[196:199], v[56:59]
	v_mfma_f32_16x16x32_f16 v[60:63], v[140:143], v[196:199], v[60:63]
	v_mfma_f32_16x16x32_f16 v[64:67], v[144:147], v[196:199], v[64:67]
	s_waitcnt vmcnt(0) lgkmcnt(0)
	s_barrier
	s_add_i32 s34, s32, 0x8000
	s_cmp_lg_u32 s32, 0x18000
	s_cselect_b32 s34, s34, 0
	v_add_u32_e32 v168, s34, v165
	v_add_u32_e32 v169, s34, v164
	v_mfma_f32_16x16x32_f16 v[68:71], v[132:135], v[238:241], v[68:71]
	ds_read_b128 v[148:151], v168 offset:16
	ds_read_b128 v[184:187], v169 offset:16
	v_mfma_f32_16x16x32_f16 v[72:75], v[136:139], v[238:241], v[72:75]
	ds_read_b128 v[152:155], v168 offset:1040
	ds_read_b128 v[188:191], v169 offset:1040
	v_mfma_f32_16x16x32_f16 v[76:79], v[140:143], v[238:241], v[76:79]
	ds_read_b128 v[156:159], v168 offset:2064
	ds_read_b128 v[192:195], v169 offset:2064
	v_mfma_f32_16x16x32_f16 v[80:83], v[144:147], v[238:241], v[80:83]
	ds_read_b128 v[160:163], v168 offset:3088
	ds_read_b128 v[196:199], v169 offset:3088
	v_mfma_f32_16x16x32_f16 v[84:87], v[132:135], v[242:245], v[84:87]
	v_mfma_f32_16x16x32_f16 v[88:91], v[136:139], v[242:245], v[88:91]
	v_mfma_f32_16x16x32_f16 v[92:95], v[140:143], v[242:245], v[92:95]
	v_mfma_f32_16x16x32_f16 v[96:99], v[144:147], v[242:245], v[96:99]
	v_mfma_f32_16x16x32_f16 v[100:103], v[132:135], v[246:249], v[100:103]
	v_mfma_f32_16x16x32_f16 v[104:107], v[136:139], v[246:249], v[104:107]
	v_mfma_f32_16x16x32_f16 v[108:111], v[140:143], v[246:249], v[108:111]
	v_mfma_f32_16x16x32_f16 v[112:115], v[144:147], v[246:249], v[112:115]
	v_mfma_f32_16x16x32_f16 v[116:119], v[132:135], v[250:253], v[116:119]
	v_mfma_f32_16x16x32_f16 v[120:123], v[136:139], v[250:253], v[120:123]
	v_mfma_f32_16x16x32_f16 v[124:127], v[140:143], v[250:253], v[124:127]
	v_mfma_f32_16x16x32_f16 v[128:131], v[144:147], v[250:253], v[128:131]
	s_waitcnt lgkmcnt(0)
	s_mov_b32 s32, s34
	v_add_u32_e32 v169, s32, v164
	v_mfma_f32_16x16x32_f16 v[4:7], v[148:151], v[184:187], v[4:7]
	ds_read_b128 v[238:241], v169 offset:4112
	v_mfma_f32_16x16x32_f16 v[8:11], v[152:155], v[184:187], v[8:11]
	ds_read_b128 v[242:245], v169 offset:5136
	v_mfma_f32_16x16x32_f16 v[12:15], v[156:159], v[184:187], v[12:15]
	ds_read_b128 v[246:249], v169 offset:6160
	v_mfma_f32_16x16x32_f16 v[16:19], v[160:163], v[184:187], v[16:19]
	ds_read_b128 v[250:253], v169 offset:7184
	v_mfma_f32_16x16x32_f16 v[20:23], v[148:151], v[188:191], v[20:23]
	v_mfma_f32_16x16x32_f16 v[24:27], v[152:155], v[188:191], v[24:27]
	v_mfma_f32_16x16x32_f16 v[28:31], v[156:159], v[188:191], v[28:31]
	v_mfma_f32_16x16x32_f16 v[32:35], v[160:163], v[188:191], v[32:35]
	v_mfma_f32_16x16x32_f16 v[36:39], v[148:151], v[192:195], v[36:39]
	v_mfma_f32_16x16x32_f16 v[40:43], v[152:155], v[192:195], v[40:43]
	v_mfma_f32_16x16x32_f16 v[44:47], v[156:159], v[192:195], v[44:47]
	v_mfma_f32_16x16x32_f16 v[48:51], v[160:163], v[192:195], v[48:51]
	v_mfma_f32_16x16x32_f16 v[52:55], v[148:151], v[196:199], v[52:55]
	v_mfma_f32_16x16x32_f16 v[56:59], v[152:155], v[196:199], v[56:59]
	v_mfma_f32_16x16x32_f16 v[60:63], v[156:159], v[196:199], v[60:63]
	v_mfma_f32_16x16x32_f16 v[64:67], v[160:163], v[196:199], v[64:67]
	s_waitcnt lgkmcnt(0)
	s_barrier
	v_mfma_f32_16x16x32_f16 v[68:71], v[148:151], v[238:241], v[68:71]
	v_mfma_f32_16x16x32_f16 v[72:75], v[152:155], v[238:241], v[72:75]
	v_mfma_f32_16x16x32_f16 v[76:79], v[156:159], v[238:241], v[76:79]
	v_mfma_f32_16x16x32_f16 v[80:83], v[160:163], v[238:241], v[80:83]
	v_mfma_f32_16x16x32_f16 v[84:87], v[148:151], v[242:245], v[84:87]
	v_mfma_f32_16x16x32_f16 v[88:91], v[152:155], v[242:245], v[88:91]
	v_mfma_f32_16x16x32_f16 v[92:95], v[156:159], v[242:245], v[92:95]
	v_mfma_f32_16x16x32_f16 v[96:99], v[160:163], v[242:245], v[96:99]
	v_mfma_f32_16x16x32_f16 v[100:103], v[148:151], v[246:249], v[100:103]
	v_mfma_f32_16x16x32_f16 v[104:107], v[152:155], v[246:249], v[104:107]
	v_mfma_f32_16x16x32_f16 v[108:111], v[156:159], v[246:249], v[108:111]
	v_mfma_f32_16x16x32_f16 v[112:115], v[160:163], v[246:249], v[112:115]
	v_mfma_f32_16x16x32_f16 v[116:119], v[148:151], v[250:253], v[116:119]
	v_mfma_f32_16x16x32_f16 v[120:123], v[152:155], v[250:253], v[120:123]
	v_mfma_f32_16x16x32_f16 v[124:127], v[156:159], v[250:253], v[124:127]
	v_mfma_f32_16x16x32_f16 v[128:131], v[160:163], v[250:253], v[128:131]
	s_sub_u32 s77, s35, 0x1000
	s_lshr_b32 s77, s77, 12
	s_add_u32 s77, s77, 1
	s_cmp_lt_u32 s35, 0x1000
	s_cselect_b32 s77, 0, s77
	s_mul_i32 s77, s77, 0x6000
	s_add_u32 s68, s44, s77
	s_addc_u32 s69, s45, 0
	s_add_u32 s68, s68, 0xfa10600
	s_addc_u32 s69, s69, 0
	s_lshl_b32 s82, s35, 11
	s_add_u32 s80, s46, s82
	s_addc_u32 s81, s47, 0
	s_lshl_b32 s82, s30, 1
	s_add_u32 s80, s80, s82
	s_addc_u32 s81, s81, 0
	v_and_b32_e32 v172, 15, v200
	v_bfe_u32 v173, v200, 4, 2
	v_bfe_u32 v174, v200, 6, 2
	v_bfe_u32 v175, v200, 8, 1
	v_lshlrev_b32_e32 v176, 6, v174
	v_lshl_or_b32 v176, v173, 2, v176
	v_lshl_or_b32 v175, v175, 7, v172
	v_lshlrev_b32_e32 v175, 11, v175
	v_lshl_add_u32 v177, v176, 1, v175
	v_add_u32_e32 v176, s30, v176
	v_lshlrev_b32_e32 v176, 2, v176
	global_load_dwordx4 v[132:135], v176, s[68:69]
	global_load_dwordx4 v[136:139], v176, s[68:69] offset:64
	global_load_dwordx4 v[140:143], v176, s[68:69] offset:128
	global_load_dwordx4 v[144:147], v176, s[68:69] offset:192
	v_and_b32_e32 v172, 1, v173
	v_mul_u32_u24_e32 v172, 24, v172
	v_add_u32_e32 v177, v177, v172
	v_mov_b32_e32 v178, v177
	global_load_dwordx4 v[184:187], v178, s[80:81]
	global_load_dwordx4 v[188:191], v178, s[80:81] offset:64
	v_add_u32_e32 v178, 0x8000, v178
	global_load_dwordx4 v[238:241], v178, s[80:81]
	global_load_dwordx4 v[242:245], v178, s[80:81] offset:64
	s_waitcnt vmcnt(3)
	v_permlane16_swap_b32_e32 v184, v186
	v_permlane16_swap_b32_e32 v185, v187
	v_cvt_f32_f16_e32 v164, v184
	v_cvt_f32_f16_sdwa v165, v184 dst_sel:DWORD dst_unused:UNUSED_PAD src0_sel:WORD_1
	v_cvt_f32_f16_e32 v166, v185
	v_cvt_f32_f16_sdwa v167, v185 dst_sel:DWORD dst_unused:UNUSED_PAD src0_sel:WORD_1
	v_pk_mul_f32 v[164:165], v[164:165], s[84:85] op_sel_hi:[1,0]
	v_pk_mul_f32 v[166:167], v[166:167], s[84:85] op_sel_hi:[1,0]
	v_pk_fma_f32 v[4:5], v[4:5], v[132:133], v[164:165]
	v_pk_fma_f32 v[6:7], v[6:7], v[134:135], v[166:167]
	v_cvt_pk_f16_f32 v172, v4, v5
	v_cvt_pk_f16_f32 v173, v6, v7
	v_cvt_f32_f16_e32 v164, v186
	v_cvt_f32_f16_sdwa v165, v186 dst_sel:DWORD dst_unused:UNUSED_PAD src0_sel:WORD_1
	v_cvt_f32_f16_e32 v166, v187
	v_cvt_f32_f16_sdwa v167, v187 dst_sel:DWORD dst_unused:UNUSED_PAD src0_sel:WORD_1
	v_pk_mul_f32 v[164:165], v[164:165], s[84:85] op_sel_hi:[1,0]
	v_pk_mul_f32 v[166:167], v[166:167], s[84:85] op_sel_hi:[1,0]
	v_pk_fma_f32 v[8:9], v[8:9], v[136:137], v[164:165]
	v_pk_fma_f32 v[10:11], v[10:11], v[138:139], v[166:167]
	v_cvt_pk_f16_f32 v174, v8, v9
	v_cvt_pk_f16_f32 v175, v10, v11
	s_nop 1
	v_permlane16_swap_b32_e32 v172, v174
	v_permlane16_swap_b32_e32 v173, v175
	global_store_dwordx4 v177, v[172:175], s[80:81]
	s_waitcnt vmcnt(3)
	v_permlane16_swap_b32_e32 v188, v190
	v_permlane16_swap_b32_e32 v189, v191
	v_cvt_f32_f16_e32 v164, v188
	v_cvt_f32_f16_sdwa v165, v188 dst_sel:DWORD dst_unused:UNUSED_PAD src0_sel:WORD_1
	v_cvt_f32_f16_e32 v166, v189
	v_cvt_f32_f16_sdwa v167, v189 dst_sel:DWORD dst_unused:UNUSED_PAD src0_sel:WORD_1
	v_pk_mul_f32 v[164:165], v[164:165], s[84:85] op_sel_hi:[1,0]
	v_pk_mul_f32 v[166:167], v[166:167], s[84:85] op_sel_hi:[1,0]
	v_pk_fma_f32 v[12:13], v[12:13], v[140:141], v[164:165]
	v_pk_fma_f32 v[14:15], v[14:15], v[142:143], v[166:167]
	v_cvt_pk_f16_f32 v228, v12, v13
	v_cvt_pk_f16_f32 v229, v14, v15
	v_cvt_f32_f16_e32 v164, v190
	v_cvt_f32_f16_sdwa v165, v190 dst_sel:DWORD dst_unused:UNUSED_PAD src0_sel:WORD_1
	v_cvt_f32_f16_e32 v166, v191
	v_cvt_f32_f16_sdwa v167, v191 dst_sel:DWORD dst_unused:UNUSED_PAD src0_sel:WORD_1
	v_pk_mul_f32 v[164:165], v[164:165], s[84:85] op_sel_hi:[1,0]
	v_pk_mul_f32 v[166:167], v[166:167], s[84:85] op_sel_hi:[1,0]
	v_pk_fma_f32 v[16:17], v[16:17], v[144:145], v[164:165]
	v_pk_fma_f32 v[18:19], v[18:19], v[146:147], v[166:167]
	v_cvt_pk_f16_f32 v230, v16, v17
	v_cvt_pk_f16_f32 v231, v18, v19
	s_nop 1
	v_permlane16_swap_b32_e32 v228, v230
	v_permlane16_swap_b32_e32 v229, v231
	global_store_dwordx4 v177, v[228:231], s[80:81] offset:64
	v_add_u32_e32 v177, 0x8000, v177
	v_add_u32_e32 v178, 0x8000, v178
	global_load_dwordx4 v[184:187], v178, s[80:81]
	global_load_dwordx4 v[188:191], v178, s[80:81] offset:64
	s_waitcnt vmcnt(5)
	v_permlane16_swap_b32_e32 v238, v240
	v_permlane16_swap_b32_e32 v239, v241
	v_cvt_f32_f16_e32 v164, v238
	v_cvt_f32_f16_sdwa v165, v238 dst_sel:DWORD dst_unused:UNUSED_PAD src0_sel:WORD_1
	v_cvt_f32_f16_e32 v166, v239
	v_cvt_f32_f16_sdwa v167, v239 dst_sel:DWORD dst_unused:UNUSED_PAD src0_sel:WORD_1
	v_pk_mul_f32 v[164:165], v[164:165], s[84:85] op_sel_hi:[1,0]
	v_pk_mul_f32 v[166:167], v[166:167], s[84:85] op_sel_hi:[1,0]
	v_pk_fma_f32 v[20:21], v[20:21], v[132:133], v[164:165]
	v_pk_fma_f32 v[22:23], v[22:23], v[134:135], v[166:167]
	v_cvt_pk_f16_f32 v172, v20, v21
	v_cvt_pk_f16_f32 v173, v22, v23
	v_cvt_f32_f16_e32 v164, v240
	v_cvt_f32_f16_sdwa v165, v240 dst_sel:DWORD dst_unused:UNUSED_PAD src0_sel:WORD_1
	v_cvt_f32_f16_e32 v166, v241
	v_cvt_f32_f16_sdwa v167, v241 dst_sel:DWORD dst_unused:UNUSED_PAD src0_sel:WORD_1
	v_pk_mul_f32 v[164:165], v[164:165], s[84:85] op_sel_hi:[1,0]
	v_pk_mul_f32 v[166:167], v[166:167], s[84:85] op_sel_hi:[1,0]
	v_pk_fma_f32 v[24:25], v[24:25], v[136:137], v[164:165]
	v_pk_fma_f32 v[26:27], v[26:27], v[138:139], v[166:167]
	v_cvt_pk_f16_f32 v174, v24, v25
	v_cvt_pk_f16_f32 v175, v26, v27
	s_nop 1
	v_permlane16_swap_b32_e32 v172, v174
	v_permlane16_swap_b32_e32 v173, v175
	global_store_dwordx4 v177, v[172:175], s[80:81]
	s_waitcnt vmcnt(5)
	v_permlane16_swap_b32_e32 v242, v244
	v_permlane16_swap_b32_e32 v243, v245
	v_cvt_f32_f16_e32 v164, v242
	v_cvt_f32_f16_sdwa v165, v242 dst_sel:DWORD dst_unused:UNUSED_PAD src0_sel:WORD_1
	v_cvt_f32_f16_e32 v166, v243
	v_cvt_f32_f16_sdwa v167, v243 dst_sel:DWORD dst_unused:UNUSED_PAD src0_sel:WORD_1
	v_pk_mul_f32 v[164:165], v[164:165], s[84:85] op_sel_hi:[1,0]
	v_pk_mul_f32 v[166:167], v[166:167], s[84:85] op_sel_hi:[1,0]
	v_pk_fma_f32 v[28:29], v[28:29], v[140:141], v[164:165]
	v_pk_fma_f32 v[30:31], v[30:31], v[142:143], v[166:167]
	v_cvt_pk_f16_f32 v228, v28, v29
	v_cvt_pk_f16_f32 v229, v30, v31
	v_cvt_f32_f16_e32 v164, v244
	v_cvt_f32_f16_sdwa v165, v244 dst_sel:DWORD dst_unused:UNUSED_PAD src0_sel:WORD_1
	v_cvt_f32_f16_e32 v166, v245
	v_cvt_f32_f16_sdwa v167, v245 dst_sel:DWORD dst_unused:UNUSED_PAD src0_sel:WORD_1
	v_pk_mul_f32 v[164:165], v[164:165], s[84:85] op_sel_hi:[1,0]
	v_pk_mul_f32 v[166:167], v[166:167], s[84:85] op_sel_hi:[1,0]
	v_pk_fma_f32 v[32:33], v[32:33], v[144:145], v[164:165]
	v_pk_fma_f32 v[34:35], v[34:35], v[146:147], v[166:167]
	v_cvt_pk_f16_f32 v230, v32, v33
	v_cvt_pk_f16_f32 v231, v34, v35
	s_nop 1
	v_permlane16_swap_b32_e32 v228, v230
	v_permlane16_swap_b32_e32 v229, v231
	global_store_dwordx4 v177, v[228:231], s[80:81] offset:64
	v_add_u32_e32 v177, 0x8000, v177
	v_add_u32_e32 v178, 0x8000, v178
	global_load_dwordx4 v[238:241], v178, s[80:81]
	global_load_dwordx4 v[242:245], v178, s[80:81] offset:64
	s_waitcnt vmcnt(5)
	v_permlane16_swap_b32_e32 v184, v186
	v_permlane16_swap_b32_e32 v185, v187
	v_cvt_f32_f16_e32 v164, v184
	v_cvt_f32_f16_sdwa v165, v184 dst_sel:DWORD dst_unused:UNUSED_PAD src0_sel:WORD_1
	v_cvt_f32_f16_e32 v166, v185
	v_cvt_f32_f16_sdwa v167, v185 dst_sel:DWORD dst_unused:UNUSED_PAD src0_sel:WORD_1
	v_pk_mul_f32 v[164:165], v[164:165], s[84:85] op_sel_hi:[1,0]
	v_pk_mul_f32 v[166:167], v[166:167], s[84:85] op_sel_hi:[1,0]
	v_pk_fma_f32 v[36:37], v[36:37], v[132:133], v[164:165]
	v_pk_fma_f32 v[38:39], v[38:39], v[134:135], v[166:167]
	v_cvt_pk_f16_f32 v172, v36, v37
	v_cvt_pk_f16_f32 v173, v38, v39
	v_cvt_f32_f16_e32 v164, v186
	v_cvt_f32_f16_sdwa v165, v186 dst_sel:DWORD dst_unused:UNUSED_PAD src0_sel:WORD_1
	v_cvt_f32_f16_e32 v166, v187
	v_cvt_f32_f16_sdwa v167, v187 dst_sel:DWORD dst_unused:UNUSED_PAD src0_sel:WORD_1
	v_pk_mul_f32 v[164:165], v[164:165], s[84:85] op_sel_hi:[1,0]
	v_pk_mul_f32 v[166:167], v[166:167], s[84:85] op_sel_hi:[1,0]
	v_pk_fma_f32 v[40:41], v[40:41], v[136:137], v[164:165]
	v_pk_fma_f32 v[42:43], v[42:43], v[138:139], v[166:167]
	v_cvt_pk_f16_f32 v174, v40, v41
	v_cvt_pk_f16_f32 v175, v42, v43
	s_nop 1
	v_permlane16_swap_b32_e32 v172, v174
	v_permlane16_swap_b32_e32 v173, v175
	global_store_dwordx4 v177, v[172:175], s[80:81]
	s_waitcnt vmcnt(5)
	v_permlane16_swap_b32_e32 v188, v190
	v_permlane16_swap_b32_e32 v189, v191
	v_cvt_f32_f16_e32 v164, v188
	v_cvt_f32_f16_sdwa v165, v188 dst_sel:DWORD dst_unused:UNUSED_PAD src0_sel:WORD_1
	v_cvt_f32_f16_e32 v166, v189
	v_cvt_f32_f16_sdwa v167, v189 dst_sel:DWORD dst_unused:UNUSED_PAD src0_sel:WORD_1
	v_pk_mul_f32 v[164:165], v[164:165], s[84:85] op_sel_hi:[1,0]
	v_pk_mul_f32 v[166:167], v[166:167], s[84:85] op_sel_hi:[1,0]
	v_pk_fma_f32 v[44:45], v[44:45], v[140:141], v[164:165]
	v_pk_fma_f32 v[46:47], v[46:47], v[142:143], v[166:167]
	v_cvt_pk_f16_f32 v228, v44, v45
	v_cvt_pk_f16_f32 v229, v46, v47
	v_cvt_f32_f16_e32 v164, v190
	v_cvt_f32_f16_sdwa v165, v190 dst_sel:DWORD dst_unused:UNUSED_PAD src0_sel:WORD_1
	v_cvt_f32_f16_e32 v166, v191
	v_cvt_f32_f16_sdwa v167, v191 dst_sel:DWORD dst_unused:UNUSED_PAD src0_sel:WORD_1
	v_pk_mul_f32 v[164:165], v[164:165], s[84:85] op_sel_hi:[1,0]
	v_pk_mul_f32 v[166:167], v[166:167], s[84:85] op_sel_hi:[1,0]
	v_pk_fma_f32 v[48:49], v[48:49], v[144:145], v[164:165]
	v_pk_fma_f32 v[50:51], v[50:51], v[146:147], v[166:167]
	v_cvt_pk_f16_f32 v230, v48, v49
	v_cvt_pk_f16_f32 v231, v50, v51
	s_nop 1
	v_permlane16_swap_b32_e32 v228, v230
	v_permlane16_swap_b32_e32 v229, v231
	global_store_dwordx4 v177, v[228:231], s[80:81] offset:64
	v_add_u32_e32 v177, 0x8000, v177
	v_add_u32_e32 v178, 0x8000, v178
	global_load_dwordx4 v[184:187], v178, s[80:81]
	global_load_dwordx4 v[188:191], v178, s[80:81] offset:64
	s_waitcnt vmcnt(5)
	v_permlane16_swap_b32_e32 v238, v240
	v_permlane16_swap_b32_e32 v239, v241
	v_cvt_f32_f16_e32 v164, v238
	v_cvt_f32_f16_sdwa v165, v238 dst_sel:DWORD dst_unused:UNUSED_PAD src0_sel:WORD_1
	v_cvt_f32_f16_e32 v166, v239
	v_cvt_f32_f16_sdwa v167, v239 dst_sel:DWORD dst_unused:UNUSED_PAD src0_sel:WORD_1
	v_pk_mul_f32 v[164:165], v[164:165], s[84:85] op_sel_hi:[1,0]
	v_pk_mul_f32 v[166:167], v[166:167], s[84:85] op_sel_hi:[1,0]
	v_pk_fma_f32 v[52:53], v[52:53], v[132:133], v[164:165]
	v_pk_fma_f32 v[54:55], v[54:55], v[134:135], v[166:167]
	v_cvt_pk_f16_f32 v172, v52, v53
	v_cvt_pk_f16_f32 v173, v54, v55
	v_cvt_f32_f16_e32 v164, v240
	v_cvt_f32_f16_sdwa v165, v240 dst_sel:DWORD dst_unused:UNUSED_PAD src0_sel:WORD_1
	v_cvt_f32_f16_e32 v166, v241
	v_cvt_f32_f16_sdwa v167, v241 dst_sel:DWORD dst_unused:UNUSED_PAD src0_sel:WORD_1
	v_pk_mul_f32 v[164:165], v[164:165], s[84:85] op_sel_hi:[1,0]
	v_pk_mul_f32 v[166:167], v[166:167], s[84:85] op_sel_hi:[1,0]
	v_pk_fma_f32 v[56:57], v[56:57], v[136:137], v[164:165]
	v_pk_fma_f32 v[58:59], v[58:59], v[138:139], v[166:167]
	v_cvt_pk_f16_f32 v174, v56, v57
	v_cvt_pk_f16_f32 v175, v58, v59
	s_nop 1
	v_permlane16_swap_b32_e32 v172, v174
	v_permlane16_swap_b32_e32 v173, v175
	global_store_dwordx4 v177, v[172:175], s[80:81]
	s_waitcnt vmcnt(5)
	v_permlane16_swap_b32_e32 v242, v244
	v_permlane16_swap_b32_e32 v243, v245
	v_cvt_f32_f16_e32 v164, v242
	v_cvt_f32_f16_sdwa v165, v242 dst_sel:DWORD dst_unused:UNUSED_PAD src0_sel:WORD_1
	v_cvt_f32_f16_e32 v166, v243
	v_cvt_f32_f16_sdwa v167, v243 dst_sel:DWORD dst_unused:UNUSED_PAD src0_sel:WORD_1
	v_pk_mul_f32 v[164:165], v[164:165], s[84:85] op_sel_hi:[1,0]
	v_pk_mul_f32 v[166:167], v[166:167], s[84:85] op_sel_hi:[1,0]
	v_pk_fma_f32 v[60:61], v[60:61], v[140:141], v[164:165]
	v_pk_fma_f32 v[62:63], v[62:63], v[142:143], v[166:167]
	v_cvt_pk_f16_f32 v228, v60, v61
	v_cvt_pk_f16_f32 v229, v62, v63
	v_cvt_f32_f16_e32 v164, v244
	v_cvt_f32_f16_sdwa v165, v244 dst_sel:DWORD dst_unused:UNUSED_PAD src0_sel:WORD_1
	v_cvt_f32_f16_e32 v166, v245
	v_cvt_f32_f16_sdwa v167, v245 dst_sel:DWORD dst_unused:UNUSED_PAD src0_sel:WORD_1
	v_pk_mul_f32 v[164:165], v[164:165], s[84:85] op_sel_hi:[1,0]
	v_pk_mul_f32 v[166:167], v[166:167], s[84:85] op_sel_hi:[1,0]
	v_pk_fma_f32 v[64:65], v[64:65], v[144:145], v[164:165]
	v_pk_fma_f32 v[66:67], v[66:67], v[146:147], v[166:167]
	v_cvt_pk_f16_f32 v230, v64, v65
	v_cvt_pk_f16_f32 v231, v66, v67
	s_nop 1
	v_permlane16_swap_b32_e32 v228, v230
	v_permlane16_swap_b32_e32 v229, v231
	global_store_dwordx4 v177, v[228:231], s[80:81] offset:64
	v_add_u32_e32 v177, 0x8000, v177
	v_add_u32_e32 v178, 0x8000, v178
	global_load_dwordx4 v[238:241], v178, s[80:81]
	global_load_dwordx4 v[242:245], v178, s[80:81] offset:64
	s_waitcnt vmcnt(5)
	v_permlane16_swap_b32_e32 v184, v186
	v_permlane16_swap_b32_e32 v185, v187
	v_cvt_f32_f16_e32 v164, v184
	v_cvt_f32_f16_sdwa v165, v184 dst_sel:DWORD dst_unused:UNUSED_PAD src0_sel:WORD_1
	v_cvt_f32_f16_e32 v166, v185
	v_cvt_f32_f16_sdwa v167, v185 dst_sel:DWORD dst_unused:UNUSED_PAD src0_sel:WORD_1
	v_pk_mul_f32 v[164:165], v[164:165], s[84:85] op_sel_hi:[1,0]
	v_pk_mul_f32 v[166:167], v[166:167], s[84:85] op_sel_hi:[1,0]
	v_pk_fma_f32 v[68:69], v[68:69], v[132:133], v[164:165]
	v_pk_fma_f32 v[70:71], v[70:71], v[134:135], v[166:167]
	v_cvt_pk_f16_f32 v172, v68, v69
	v_cvt_pk_f16_f32 v173, v70, v71
	v_cvt_f32_f16_e32 v164, v186
	v_cvt_f32_f16_sdwa v165, v186 dst_sel:DWORD dst_unused:UNUSED_PAD src0_sel:WORD_1
	v_cvt_f32_f16_e32 v166, v187
	v_cvt_f32_f16_sdwa v167, v187 dst_sel:DWORD dst_unused:UNUSED_PAD src0_sel:WORD_1
	v_pk_mul_f32 v[164:165], v[164:165], s[84:85] op_sel_hi:[1,0]
	v_pk_mul_f32 v[166:167], v[166:167], s[84:85] op_sel_hi:[1,0]
	v_pk_fma_f32 v[72:73], v[72:73], v[136:137], v[164:165]
	v_pk_fma_f32 v[74:75], v[74:75], v[138:139], v[166:167]
	v_cvt_pk_f16_f32 v174, v72, v73
	v_cvt_pk_f16_f32 v175, v74, v75
	s_nop 1
	v_permlane16_swap_b32_e32 v172, v174
	v_permlane16_swap_b32_e32 v173, v175
	global_store_dwordx4 v177, v[172:175], s[80:81]
	s_waitcnt vmcnt(5)
	v_permlane16_swap_b32_e32 v188, v190
	v_permlane16_swap_b32_e32 v189, v191
	v_cvt_f32_f16_e32 v164, v188
	v_cvt_f32_f16_sdwa v165, v188 dst_sel:DWORD dst_unused:UNUSED_PAD src0_sel:WORD_1
	v_cvt_f32_f16_e32 v166, v189
	v_cvt_f32_f16_sdwa v167, v189 dst_sel:DWORD dst_unused:UNUSED_PAD src0_sel:WORD_1
	v_pk_mul_f32 v[164:165], v[164:165], s[84:85] op_sel_hi:[1,0]
	v_pk_mul_f32 v[166:167], v[166:167], s[84:85] op_sel_hi:[1,0]
	v_pk_fma_f32 v[76:77], v[76:77], v[140:141], v[164:165]
	v_pk_fma_f32 v[78:79], v[78:79], v[142:143], v[166:167]
	v_cvt_pk_f16_f32 v228, v76, v77
	v_cvt_pk_f16_f32 v229, v78, v79
	v_cvt_f32_f16_e32 v164, v190
	v_cvt_f32_f16_sdwa v165, v190 dst_sel:DWORD dst_unused:UNUSED_PAD src0_sel:WORD_1
	v_cvt_f32_f16_e32 v166, v191
	v_cvt_f32_f16_sdwa v167, v191 dst_sel:DWORD dst_unused:UNUSED_PAD src0_sel:WORD_1
	v_pk_mul_f32 v[164:165], v[164:165], s[84:85] op_sel_hi:[1,0]
	v_pk_mul_f32 v[166:167], v[166:167], s[84:85] op_sel_hi:[1,0]
	v_pk_fma_f32 v[80:81], v[80:81], v[144:145], v[164:165]
	v_pk_fma_f32 v[82:83], v[82:83], v[146:147], v[166:167]
	v_cvt_pk_f16_f32 v230, v80, v81
	v_cvt_pk_f16_f32 v231, v82, v83
	s_nop 1
	v_permlane16_swap_b32_e32 v228, v230
	v_permlane16_swap_b32_e32 v229, v231
	global_store_dwordx4 v177, v[228:231], s[80:81] offset:64
	v_add_u32_e32 v177, 0x8000, v177
	v_add_u32_e32 v178, 0x8000, v178
	global_load_dwordx4 v[184:187], v178, s[80:81]
	global_load_dwordx4 v[188:191], v178, s[80:81] offset:64
	s_waitcnt vmcnt(5)
	v_permlane16_swap_b32_e32 v238, v240
	v_permlane16_swap_b32_e32 v239, v241
	v_cvt_f32_f16_e32 v164, v238
	v_cvt_f32_f16_sdwa v165, v238 dst_sel:DWORD dst_unused:UNUSED_PAD src0_sel:WORD_1
	v_cvt_f32_f16_e32 v166, v239
	v_cvt_f32_f16_sdwa v167, v239 dst_sel:DWORD dst_unused:UNUSED_PAD src0_sel:WORD_1
	v_pk_mul_f32 v[164:165], v[164:165], s[84:85] op_sel_hi:[1,0]
	v_pk_mul_f32 v[166:167], v[166:167], s[84:85] op_sel_hi:[1,0]
	v_pk_fma_f32 v[84:85], v[84:85], v[132:133], v[164:165]
	v_pk_fma_f32 v[86:87], v[86:87], v[134:135], v[166:167]
	v_cvt_pk_f16_f32 v172, v84, v85
	v_cvt_pk_f16_f32 v173, v86, v87
	v_cvt_f32_f16_e32 v164, v240
	v_cvt_f32_f16_sdwa v165, v240 dst_sel:DWORD dst_unused:UNUSED_PAD src0_sel:WORD_1
	v_cvt_f32_f16_e32 v166, v241
	v_cvt_f32_f16_sdwa v167, v241 dst_sel:DWORD dst_unused:UNUSED_PAD src0_sel:WORD_1
	v_pk_mul_f32 v[164:165], v[164:165], s[84:85] op_sel_hi:[1,0]
	v_pk_mul_f32 v[166:167], v[166:167], s[84:85] op_sel_hi:[1,0]
	v_pk_fma_f32 v[88:89], v[88:89], v[136:137], v[164:165]
	v_pk_fma_f32 v[90:91], v[90:91], v[138:139], v[166:167]
	v_cvt_pk_f16_f32 v174, v88, v89
	v_cvt_pk_f16_f32 v175, v90, v91
	s_nop 1
	v_permlane16_swap_b32_e32 v172, v174
	v_permlane16_swap_b32_e32 v173, v175
	global_store_dwordx4 v177, v[172:175], s[80:81]
	s_waitcnt vmcnt(5)
	v_permlane16_swap_b32_e32 v242, v244
	v_permlane16_swap_b32_e32 v243, v245
	v_cvt_f32_f16_e32 v164, v242
	v_cvt_f32_f16_sdwa v165, v242 dst_sel:DWORD dst_unused:UNUSED_PAD src0_sel:WORD_1
	v_cvt_f32_f16_e32 v166, v243
	v_cvt_f32_f16_sdwa v167, v243 dst_sel:DWORD dst_unused:UNUSED_PAD src0_sel:WORD_1
	v_pk_mul_f32 v[164:165], v[164:165], s[84:85] op_sel_hi:[1,0]
	v_pk_mul_f32 v[166:167], v[166:167], s[84:85] op_sel_hi:[1,0]
	v_pk_fma_f32 v[92:93], v[92:93], v[140:141], v[164:165]
	v_pk_fma_f32 v[94:95], v[94:95], v[142:143], v[166:167]
	v_cvt_pk_f16_f32 v228, v92, v93
	v_cvt_pk_f16_f32 v229, v94, v95
	v_cvt_f32_f16_e32 v164, v244
	v_cvt_f32_f16_sdwa v165, v244 dst_sel:DWORD dst_unused:UNUSED_PAD src0_sel:WORD_1
	v_cvt_f32_f16_e32 v166, v245
	v_cvt_f32_f16_sdwa v167, v245 dst_sel:DWORD dst_unused:UNUSED_PAD src0_sel:WORD_1
	v_pk_mul_f32 v[164:165], v[164:165], s[84:85] op_sel_hi:[1,0]
	v_pk_mul_f32 v[166:167], v[166:167], s[84:85] op_sel_hi:[1,0]
	v_pk_fma_f32 v[96:97], v[96:97], v[144:145], v[164:165]
	v_pk_fma_f32 v[98:99], v[98:99], v[146:147], v[166:167]
	v_cvt_pk_f16_f32 v230, v96, v97
	v_cvt_pk_f16_f32 v231, v98, v99
	s_nop 1
	v_permlane16_swap_b32_e32 v228, v230
	v_permlane16_swap_b32_e32 v229, v231
	global_store_dwordx4 v177, v[228:231], s[80:81] offset:64
	v_add_u32_e32 v177, 0x8000, v177
	v_add_u32_e32 v178, 0x8000, v178
	global_load_dwordx4 v[238:241], v178, s[80:81]
	global_load_dwordx4 v[242:245], v178, s[80:81] offset:64
	s_waitcnt vmcnt(5)
	v_permlane16_swap_b32_e32 v184, v186
	v_permlane16_swap_b32_e32 v185, v187
	v_cvt_f32_f16_e32 v164, v184
	v_cvt_f32_f16_sdwa v165, v184 dst_sel:DWORD dst_unused:UNUSED_PAD src0_sel:WORD_1
	v_cvt_f32_f16_e32 v166, v185
	v_cvt_f32_f16_sdwa v167, v185 dst_sel:DWORD dst_unused:UNUSED_PAD src0_sel:WORD_1
	v_pk_mul_f32 v[164:165], v[164:165], s[84:85] op_sel_hi:[1,0]
	v_pk_mul_f32 v[166:167], v[166:167], s[84:85] op_sel_hi:[1,0]
	v_pk_fma_f32 v[100:101], v[100:101], v[132:133], v[164:165]
	v_pk_fma_f32 v[102:103], v[102:103], v[134:135], v[166:167]
	v_cvt_pk_f16_f32 v172, v100, v101
	v_cvt_pk_f16_f32 v173, v102, v103
	v_cvt_f32_f16_e32 v164, v186
	v_cvt_f32_f16_sdwa v165, v186 dst_sel:DWORD dst_unused:UNUSED_PAD src0_sel:WORD_1
	v_cvt_f32_f16_e32 v166, v187
	v_cvt_f32_f16_sdwa v167, v187 dst_sel:DWORD dst_unused:UNUSED_PAD src0_sel:WORD_1
	v_pk_mul_f32 v[164:165], v[164:165], s[84:85] op_sel_hi:[1,0]
	v_pk_mul_f32 v[166:167], v[166:167], s[84:85] op_sel_hi:[1,0]
	v_pk_fma_f32 v[104:105], v[104:105], v[136:137], v[164:165]
	v_pk_fma_f32 v[106:107], v[106:107], v[138:139], v[166:167]
	v_cvt_pk_f16_f32 v174, v104, v105
	v_cvt_pk_f16_f32 v175, v106, v107
	s_nop 1
	v_permlane16_swap_b32_e32 v172, v174
	v_permlane16_swap_b32_e32 v173, v175
	global_store_dwordx4 v177, v[172:175], s[80:81]
	s_waitcnt vmcnt(5)
	v_permlane16_swap_b32_e32 v188, v190
	v_permlane16_swap_b32_e32 v189, v191
	v_cvt_f32_f16_e32 v164, v188
	v_cvt_f32_f16_sdwa v165, v188 dst_sel:DWORD dst_unused:UNUSED_PAD src0_sel:WORD_1
	v_cvt_f32_f16_e32 v166, v189
	v_cvt_f32_f16_sdwa v167, v189 dst_sel:DWORD dst_unused:UNUSED_PAD src0_sel:WORD_1
	v_pk_mul_f32 v[164:165], v[164:165], s[84:85] op_sel_hi:[1,0]
	v_pk_mul_f32 v[166:167], v[166:167], s[84:85] op_sel_hi:[1,0]
	v_pk_fma_f32 v[108:109], v[108:109], v[140:141], v[164:165]
	v_pk_fma_f32 v[110:111], v[110:111], v[142:143], v[166:167]
	v_cvt_pk_f16_f32 v228, v108, v109
	v_cvt_pk_f16_f32 v229, v110, v111
	v_cvt_f32_f16_e32 v164, v190
	v_cvt_f32_f16_sdwa v165, v190 dst_sel:DWORD dst_unused:UNUSED_PAD src0_sel:WORD_1
	v_cvt_f32_f16_e32 v166, v191
	v_cvt_f32_f16_sdwa v167, v191 dst_sel:DWORD dst_unused:UNUSED_PAD src0_sel:WORD_1
	v_pk_mul_f32 v[164:165], v[164:165], s[84:85] op_sel_hi:[1,0]
	v_pk_mul_f32 v[166:167], v[166:167], s[84:85] op_sel_hi:[1,0]
	v_pk_fma_f32 v[112:113], v[112:113], v[144:145], v[164:165]
	v_pk_fma_f32 v[114:115], v[114:115], v[146:147], v[166:167]
	v_cvt_pk_f16_f32 v230, v112, v113
	v_cvt_pk_f16_f32 v231, v114, v115
	s_nop 1
	v_permlane16_swap_b32_e32 v228, v230
	v_permlane16_swap_b32_e32 v229, v231
	global_store_dwordx4 v177, v[228:231], s[80:81] offset:64
	v_add_u32_e32 v177, 0x8000, v177
	s_waitcnt vmcnt(3)
	v_permlane16_swap_b32_e32 v238, v240
	v_permlane16_swap_b32_e32 v239, v241
	v_cvt_f32_f16_e32 v164, v238
	v_cvt_f32_f16_sdwa v165, v238 dst_sel:DWORD dst_unused:UNUSED_PAD src0_sel:WORD_1
	v_cvt_f32_f16_e32 v166, v239
	v_cvt_f32_f16_sdwa v167, v239 dst_sel:DWORD dst_unused:UNUSED_PAD src0_sel:WORD_1
	v_pk_mul_f32 v[164:165], v[164:165], s[84:85] op_sel_hi:[1,0]
	v_pk_mul_f32 v[166:167], v[166:167], s[84:85] op_sel_hi:[1,0]
	v_pk_fma_f32 v[116:117], v[116:117], v[132:133], v[164:165]
	v_pk_fma_f32 v[118:119], v[118:119], v[134:135], v[166:167]
	v_cvt_pk_f16_f32 v172, v116, v117
	v_cvt_pk_f16_f32 v173, v118, v119
	v_cvt_f32_f16_e32 v164, v240
	v_cvt_f32_f16_sdwa v165, v240 dst_sel:DWORD dst_unused:UNUSED_PAD src0_sel:WORD_1
	v_cvt_f32_f16_e32 v166, v241
	v_cvt_f32_f16_sdwa v167, v241 dst_sel:DWORD dst_unused:UNUSED_PAD src0_sel:WORD_1
	v_pk_mul_f32 v[164:165], v[164:165], s[84:85] op_sel_hi:[1,0]
	v_pk_mul_f32 v[166:167], v[166:167], s[84:85] op_sel_hi:[1,0]
	v_pk_fma_f32 v[120:121], v[120:121], v[136:137], v[164:165]
	v_pk_fma_f32 v[122:123], v[122:123], v[138:139], v[166:167]
	v_cvt_pk_f16_f32 v174, v120, v121
	v_cvt_pk_f16_f32 v175, v122, v123
	s_nop 1
	v_permlane16_swap_b32_e32 v172, v174
	v_permlane16_swap_b32_e32 v173, v175
	global_store_dwordx4 v177, v[172:175], s[80:81]
	s_waitcnt vmcnt(3)
	v_permlane16_swap_b32_e32 v242, v244
	v_permlane16_swap_b32_e32 v243, v245
	v_cvt_f32_f16_e32 v164, v242
	v_cvt_f32_f16_sdwa v165, v242 dst_sel:DWORD dst_unused:UNUSED_PAD src0_sel:WORD_1
	v_cvt_f32_f16_e32 v166, v243
	v_cvt_f32_f16_sdwa v167, v243 dst_sel:DWORD dst_unused:UNUSED_PAD src0_sel:WORD_1
	v_pk_mul_f32 v[164:165], v[164:165], s[84:85] op_sel_hi:[1,0]
	v_pk_mul_f32 v[166:167], v[166:167], s[84:85] op_sel_hi:[1,0]
	v_pk_fma_f32 v[124:125], v[124:125], v[140:141], v[164:165]
	v_pk_fma_f32 v[126:127], v[126:127], v[142:143], v[166:167]
	v_cvt_pk_f16_f32 v228, v124, v125
	v_cvt_pk_f16_f32 v229, v126, v127
	v_cvt_f32_f16_e32 v164, v244
	v_cvt_f32_f16_sdwa v165, v244 dst_sel:DWORD dst_unused:UNUSED_PAD src0_sel:WORD_1
	v_cvt_f32_f16_e32 v166, v245
	v_cvt_f32_f16_sdwa v167, v245 dst_sel:DWORD dst_unused:UNUSED_PAD src0_sel:WORD_1
	v_pk_mul_f32 v[164:165], v[164:165], s[84:85] op_sel_hi:[1,0]
	v_pk_mul_f32 v[166:167], v[166:167], s[84:85] op_sel_hi:[1,0]
	v_pk_fma_f32 v[128:129], v[128:129], v[144:145], v[164:165]
	v_pk_fma_f32 v[130:131], v[130:131], v[146:147], v[166:167]
	v_cvt_pk_f16_f32 v230, v128, v129
	v_cvt_pk_f16_f32 v231, v130, v131
	s_nop 1
	v_permlane16_swap_b32_e32 v228, v230
	v_permlane16_swap_b32_e32 v229, v231
	global_store_dwordx4 v177, v[228:231], s[80:81] offset:64
	s_nop 1
	s_branch .LBB0_814
